# C units: one barrier per KV tile (V staged one half-step later), tail V write
# baseline (speedup 1.0000x reference)
;     ...
;   int tid_ = wave0 * 64 + lane_id_v();
;   const int tid = tid_, wid = tid >> 6, lane = tid & 63, r32 = lane & 31, hi = lane >> 5;
;   char* V_lds = lds; char* K_lds = lds + LDS_K_OFF;
;   float* ws = (float*)(lds + LDS_WS_OFF) + wid * 64; float* li_l = ws; float* al_l = ws + 32;
;   float* tbl_l = (float*)(lds + LDS_TBL_OFF);
;   __syncthreads();
;   if constexpr (BIAS) { for (int i = tid; i < TBLN; i += 512) tbl_l[i] = tblg[i]; }
;   float mC = 0.f, l_reg = 0, nm_cur = 0.f; f32x16 o[4] = {}; f32x16 negm = {}; bf16x8 qr[NDQ - NQL];
;   const bf16_t* Qw = Qb + (long)(wid * QBLK + r32) * ldq + hi * 8;
;   char* qls = lds + LDS_Q_OFF + wid * 8192 + lane * 16;
; #pragma unroll
;   for (int d0 = 0; d0 < NDQ - NQL; ++d0) qr[d0] = *reinterpret_cast<const bf16x8*>(Qw + d0 * 16);
;   if constexpr (ROPEQ) {
;     static_assert(NDQ == 12 && NQL >= 4, "ROPEQ: MLA layout");
; #pragma unroll
;     for (int d0 = NDQ - NQL; d0 < 8; ++d0) *reinterpret_cast<bf16x8*>(qls + (d0 - (NDQ - NQL)) * 1024) = *reinterpret_cast<const bf16x8*>(Qw + d0 * 16);
;     const int qrow = q0 + wid * QBLK + r32;
; #pragma unroll
;     for (int pr = 0; pr < 2; ++pr) {
;       const bf16x8 xa = *reinterpret_cast<const bf16x8*>(Qw + (8 + pr) * 16), xb = *reinterpret_cast<const bf16x8*>(Qw + (10 + pr) * 16);
;       const float* cp = cosp + (size_t)qrow * 32 + pr * 16 + hi * 8; const float* sp = sinp + (size_t)qrow * 32 + pr * 16 + hi * 8;
;       const f32x4 c0 = *(const f32x4*)cp, c1 = *(const f32x4*)(cp + 4), s0 = *(const f32x4*)sp, s1 = *(const f32x4*)(sp + 4);
;       float ya[8], yb[8];
; #pragma unroll
;       for (int t = 0; t < 8; ++t) { const float x1 = bf2f((unsigned short)xa[t]), x2 = bf2f((unsigned short)xb[t]); const float c = t < 4 ? c0[t & 3] : c1[t & 3], sn = t < 4 ? s0[t & 3] : s1[t & 3];
;         ya[t] = x1 * c - x2 * sn; yb[t] = x2 * c + x1 * sn; }
;       u32x4 wa = {pk2(ya[0], ya[1]), pk2(ya[2], ya[3]), pk2(ya[4], ya[5]), pk2(ya[6], ya[7])}, wb = {pk2(yb[0], yb[1]), pk2(yb[2], yb[3]), pk2(yb[4], yb[5]), pk2(yb[6], yb[7])};
;       *reinterpret_cast<u32x4*>(qls + (8 + pr - (NDQ - NQL)) * 1024) = wa; *reinterpret_cast<u32x4*>(qls + (10 + pr - (NDQ - NQL)) * 1024) = wb; }
;   } else {
; #pragma unroll
;   for (int d0 = NDQ - NQL; d0 < NDQ; ++d0) *reinterpret_cast<bf16x8*>(qls + (d0 - (NDQ - NQL)) * 1024) = *reinterpret_cast<const bf16x8*>(Qw + d0 * 16);
;   }
.LBB0_419:
	s_lshl_b32 s4, s61, 7
	s_lshl_b32 s5, s62, 3
	s_and_b32 s64, s4, 0x100
	s_lshr_b32 s4, s62, 3
	s_and_b32 s5, s5, 32
	s_add_i32 s5, s5, s4
	s_lshl_b32 s8, s5, 8
	s_ashr_i32 s9, s8, 31
	s_and_b32 s63, s62, 3
	s_lshl_b64 s[4:5], s[8:9], 10
	s_add_u32 s4, s37, s4
	s_addc_u32 s5, s44, s5
	s_lshl_b32 s6, s63, 8
	s_add_u32 s56, s4, s6
	s_addc_u32 s57, s5, 0
	s_lshl_b32 s4, s62, 7
	s_and_b32 s4, s4, 0x100
	s_add_u32 s50, s45, s4
	s_addc_u32 s51, s46, 0
	v_readlane_b32 s6, v254, 19
	s_add_u32 s58, s47, s4
	v_readlane_b32 s7, v254, 20
	s_addc_u32 s59, s60, 0
	s_mov_b64 s[4:5], -1
	s_and_b64 vcc, exec, s[6:7]
	s_cbranch_vccz .LBB0_445
	v_readlane_b32 s4, v254, 8
	v_mbcnt_lo_u32_b32 v22, -1, 0
	v_mbcnt_hi_u32_b32 v22, -1, v22
	v_mov_b64_e32 v[54:55], s[58:59]
	v_lshlrev_b32_e32 v24, 3, v22
	v_add_u32_e32 v23, s4, v22
	v_ashrrev_i32_e32 v50, 4, v23
	v_and_b32_e32 v0, 0x78, v24
	v_lshlrev_b32_e32 v0, 1, v0
	v_mad_i64_i32 v[2:3], s[4:5], v50, s55, v[54:55]
	v_lshl_add_u64 v[2:3], v[2:3], 0, v[0:1]
	s_waitcnt vmcnt(63) expcnt(7) lgkmcnt(15)
	s_barrier
	v_add_u32_e32 v18, 32, v50
	global_load_dwordx4 v[2:5], v[2:3], off
	v_ashrrev_i32_e32 v51, 31, v50
	v_mad_i64_i32 v[6:7], s[4:5], v18, s55, v[54:55]
	v_ashrrev_i32_e32 v19, 31, v18
	v_lshlrev_b64 v[52:53], 9, v[50:51]
	v_lshlrev_b64 v[14:15], 9, v[18:19]
	v_ashrrev_i32_e32 v19, 1, v23
	s_movk_i32 s4, 0xffe0
	v_lshl_add_u64 v[10:11], s[50:51], 0, v[52:53]
	v_lshl_add_u64 v[14:15], s[50:51], 0, v[14:15]
	v_bfi_b32 v20, s4, v19, v22
	v_lshl_add_u64 v[6:7], v[6:7], 0, v[0:1]
	v_lshl_add_u64 v[10:11], v[10:11], 0, v[0:1]
	v_lshl_add_u64 v[14:15], v[14:15], 0, v[0:1]
	v_ashrrev_i32_e32 v21, 31, v20
	v_bfe_u32 v196, v22, 5, 1
	global_load_dwordx4 v[6:9], v[6:7], off
	v_lshlrev_b64 v[20:21], 10, v[20:21]
	global_load_dwordx4 v[10:13], v[10:11], off
	v_lshl_add_u64 v[20:21], s[56:57], 0, v[20:21]
	global_load_dwordx4 v[14:17], v[14:15], off
	v_lshlrev_b32_e32 v182, 4, v196
	v_mov_b32_e32 v183, v1
	v_lshl_add_u64 v[20:21], v[20:21], 0, v[182:183]
	global_load_dwordx4 v[142:145], v[20:21], off
	global_load_dwordx4 v[138:141], v[20:21], off offset:32
	global_load_dwordx4 v[134:137], v[20:21], off offset:64
	global_load_dwordx4 v[130:133], v[20:21], off offset:96
	global_load_dwordx4 v[126:129], v[20:21], off offset:128
	global_load_dwordx4 v[122:125], v[20:21], off offset:160
	global_load_dwordx4 v[118:121], v[20:21], off offset:192
	global_load_dwordx4 v[114:117], v[20:21], off offset:224
	v_and_b32_e32 v20, 0x3fffffc0, v23
	s_add_i32 s4, 0, 0x14000
	v_lshl_add_u32 v179, v20, 2, s4
	v_and_b32_e32 v180, 0xffffffe0, v19
	v_and_b32_e32 v19, 0xfffff0, v50
	v_lshlrev_b32_e32 v20, 1, v50
	v_and_or_b32 v19, v20, 8, v19
	v_lshrrev_b32_e32 v20, 1, v50
	v_lshrrev_b32_e32 v19, 1, v19
	v_bfe_u32 v21, v24, 5, 2
	v_and_b32_e32 v24, 3, v50
	v_or_b32_e32 v19, v19, v21
	v_and_or_b32 v20, v20, 4, v24
	v_and_b32_e32 v25, 0xfffff0, v18
	v_lshlrev_b32_e32 v26, 1, v18
	v_lshlrev_b32_e32 v19, 9, v19
	v_lshlrev_b32_e32 v20, 6, v20
	v_and_b32_e32 v24, 48, v0
	v_and_or_b32 v25, v26, 8, v25
	v_or3_b32 v19, v19, v20, v24
	v_lshrrev_b32_e32 v25, 1, v25
	v_or_b32_e32 v21, v25, v21
	v_add_u32_e32 v201, 0, v19
	v_lshlrev_b32_e32 v21, 9, v21
	s_waitcnt vmcnt(0)
	v_and_b32_e32 v51, 63, v22
	v_or3_b32 v20, v21, v20, v24
	v_lshlrev_b32_e32 v24, 4, v22
	s_cmp_lg_u32 0, -1
	v_lshlrev_b32_e32 v21, 3, v51
	v_and_b32_e32 v24, 0xc0, v24
	v_lshlrev_b32_e32 v25, 1, v22
	s_cselect_b32 s6, 0, 0
	s_add_i32 s4, 0, 0x8000
	v_and_b32_e32 v178, 31, v22
	v_and_or_b32 v24, v21, 24, v24
	v_and_b32_e32 v25, 32, v25
	v_and_b32_e32 v21, 0x100, v21
	s_cmp_lg_u32 s4, -1
	v_and_b32_e32 v87, 15, v22
	v_bitop3_b32 v22, v196, v22, 15 bitop3:0x78
	v_or3_b32 v86, v24, v25, v21
	v_lshlrev_b32_e32 v21, 8, v178
	s_cselect_b32 s4, s4, 0
	v_lshlrev_b32_e32 v22, 4, v22
	v_add_u32_e32 v207, 0, v20
	v_add3_u32 v200, v21, s4, v22
	v_xor_b32_e32 v210, 32, v200
	v_xor_b32_e32 v211, 64, v200
	s_mov_b32 s65, -1
	v_add_u32_e32 v199, s6, v86
	s_waitcnt vmcnt(11)
	ds_write_b128 v201, v[2:5]
	v_lshlrev_b32_e32 v2, 8, v50
	v_and_b32_e32 v3, 0xf0, v23
	v_bitop3_b32 v2, v0, v2, v3 bitop3:0xde
	v_add_u32_e32 v208, 0, v2
	v_lshlrev_b32_e32 v2, 8, v18
	v_bitop3_b32 v2, v2, v0, v3 bitop3:0xf6
	v_add_u32_e32 v209, 0, v2
	s_waitcnt vmcnt(10)
	ds_write_b128 v207, v[6:9]
	s_waitcnt vmcnt(9)
	ds_write_b128 v208, v[10:13] offset:32768
	s_waitcnt vmcnt(8)
	ds_write_b128 v209, v[14:17] offset:32768
	s_waitcnt lgkmcnt(0)
	s_barrier
; __device__ __forceinline__ void qkt8_roll(f32x16& p0, f32x16& p1, const f32x16& negm, int kb, const bf16x8* qr) {
;   const int a0 = kb ^ (0 << 5); const bf16x8 x0 = lds_rd128<0>(a0), y0 = lds_rd128<8192>(a0);
;   const int a1 = kb ^ (1 << 5); const bf16x8 x1 = lds_rd128<0>(a1), y1 = lds_rd128<8192>(a1);
;   const int a2 = kb ^ (2 << 5); const bf16x8 x2 = lds_rd128<0>(a2), y2 = lds_rd128<8192>(a2);
;   asm volatile("s_waitcnt lgkmcnt(4)" ::: "memory"); SBAR_M();
;   p0 = __builtin_amdgcn_mfma_f32_32x32x16_bf16(x0, qr[0], negm, 0, 0, 0); p1 = __builtin_amdgcn_mfma_f32_32x32x16_bf16(y0, qr[0], negm, 0, 0, 0);
;   const int a3 = kb ^ (3 << 5); const bf16x8 x3 = lds_rd128<0>(a3), y3 = lds_rd128<8192>(a3);
;   asm volatile("s_waitcnt lgkmcnt(4)" ::: "memory"); SBAR_M();
;   p0 = __builtin_amdgcn_mfma_f32_32x32x16_bf16(x1, qr[1], p0, 0, 0, 0); p1 = __builtin_amdgcn_mfma_f32_32x32x16_bf16(y1, qr[1], p1, 0, 0, 0);
;   const int a4 = kb ^ (4 << 5); const bf16x8 x4 = lds_rd128<0>(a4), y4 = lds_rd128<8192>(a4);
;   asm volatile("s_waitcnt lgkmcnt(4)" ::: "memory"); SBAR_M();
;   p0 = __builtin_amdgcn_mfma_f32_32x32x16_bf16(x2, qr[2], p0, 0, 0, 0); p1 = __builtin_amdgcn_mfma_f32_32x32x16_bf16(y2, qr[2], p1, 0, 0, 0);
;   const int a5 = kb ^ (5 << 5); const bf16x8 x5 = lds_rd128<0>(a5), y5 = lds_rd128<8192>(a5);
;   asm volatile("s_waitcnt lgkmcnt(4)" ::: "memory"); SBAR_M();
;   p0 = __builtin_amdgcn_mfma_f32_32x32x16_bf16(x3, qr[3], p0, 0, 0, 0); p1 = __builtin_amdgcn_mfma_f32_32x32x16_bf16(y3, qr[3], p1, 0, 0, 0);
;   const int a6 = kb ^ (6 << 5); const bf16x8 x6 = lds_rd128<0>(a6), y6 = lds_rd128<8192>(a6);
;   asm volatile("s_waitcnt lgkmcnt(4)" ::: "memory"); SBAR_M();
;   p0 = __builtin_amdgcn_mfma_f32_32x32x16_bf16(x4, qr[4], p0, 0, 0, 0); p1 = __builtin_amdgcn_mfma_f32_32x32x16_bf16(y4, qr[4], p1, 0, 0, 0);
;   const int a7 = kb ^ (7 << 5); const bf16x8 x7 = lds_rd128<0>(a7), y7 = lds_rd128<8192>(a7);
;   asm volatile("s_waitcnt lgkmcnt(4)" ::: "memory"); SBAR_M();
;   p0 = __builtin_amdgcn_mfma_f32_32x32x16_bf16(x5, qr[5], p0, 0, 0, 0); p1 = __builtin_amdgcn_mfma_f32_32x32x16_bf16(y5, qr[5], p1, 0, 0, 0);
;   asm volatile("s_waitcnt lgkmcnt(2)" ::: "memory"); SBAR_M();
;   p0 = __builtin_amdgcn_mfma_f32_32x32x16_bf16(x6, qr[6], p0, 0, 0, 0); p1 = __builtin_amdgcn_mfma_f32_32x32x16_bf16(y6, qr[6], p1, 0, 0, 0);
	ds_read_b128 v[2:5], v200 offset:0
	ds_read_b128 v[18:21], v200 offset:0x2000
	ds_read_b128 v[56:59], v210 offset:0
	ds_read_b128 v[60:63], v210 offset:0x2000
	ds_read_b128 v[64:67], v211 offset:0
	ds_read_b128 v[68:71], v211 offset:0x2000
	s_waitcnt lgkmcnt(4)
	s_waitcnt vmcnt(7)
	v_mfma_f32_32x32x16_bf16 v[34:49], v[2:5], v[142:145], 0
	v_xor_b32_e32 v212, 0x60, v200
	ds_read_b128 v[72:75], v212 offset:0
	ds_read_b128 v[76:79], v212 offset:0x2000
	s_mov_b32 s13, s12
	s_waitcnt lgkmcnt(4)
	s_mov_b32 s14, s12
	s_mov_b32 s15, s12
	v_mfma_f32_32x32x16_bf16 v[18:33], v[18:21], v[142:145], 0
	s_mov_b32 s16, s12
	s_mov_b32 s17, s12
	s_mov_b32 s18, s12
	s_mov_b32 s19, s12
	s_mov_b32 s20, s12
	s_mov_b32 s21, s12
	s_mov_b32 s22, s12
	s_mov_b32 s23, s12
	s_mov_b32 s24, s12
	s_mov_b32 s25, s12
	s_mov_b32 s26, s12
	s_mov_b32 s27, s12
	v_mov_b64_e32 v[2:3], s[12:13]
	v_mov_b64_e32 v[4:5], s[14:15]
	v_mov_b64_e32 v[6:7], s[16:17]
	v_mov_b64_e32 v[8:9], s[18:19]
	v_mov_b64_e32 v[10:11], s[20:21]
	v_mov_b64_e32 v[12:13], s[22:23]
	v_mov_b64_e32 v[14:15], s[24:25]
	v_mov_b64_e32 v[16:17], s[26:27]
	s_waitcnt vmcnt(6)
	v_mfma_f32_32x32x16_bf16 v[34:49], v[56:59], v[138:141], v[34:49]
	v_xor_b32_e32 v213, 0x80, v200
	ds_read_b128 v[56:59], v213 offset:0
	v_mfma_f32_32x32x16_bf16 v[18:33], v[60:63], v[138:141], v[18:33]
	ds_read_b128 v[60:63], v213 offset:0x2000
	s_waitcnt lgkmcnt(4)
	s_waitcnt vmcnt(5)
	v_mfma_f32_32x32x16_bf16 v[34:49], v[64:67], v[134:137], v[34:49]
	v_xor_b32_e32 v214, 0xa0, v200
	ds_read_b128 v[64:67], v214 offset:0
	v_mfma_f32_32x32x16_bf16 v[18:33], v[68:71], v[134:137], v[18:33]
	ds_read_b128 v[68:71], v214 offset:0x2000
	s_waitcnt lgkmcnt(4)
	s_waitcnt vmcnt(4)
	v_mfma_f32_32x32x16_bf16 v[34:49], v[72:75], v[130:133], v[34:49]
	v_xor_b32_e32 v215, 0xc0, v200
	ds_read_b128 v[72:75], v215 offset:0
	v_mfma_f32_32x32x16_bf16 v[18:33], v[76:79], v[130:133], v[18:33]
	ds_read_b128 v[76:79], v215 offset:0x2000
	s_waitcnt lgkmcnt(4)
	s_waitcnt vmcnt(3)
	v_mfma_f32_32x32x16_bf16 v[34:49], v[56:59], v[126:129], v[34:49]
	v_xor_b32_e32 v216, 0xe0, v200
	ds_read_b128 v[56:59], v216 offset:0
	v_mfma_f32_32x32x16_bf16 v[18:33], v[60:63], v[126:129], v[18:33]
	ds_read_b128 v[60:63], v216 offset:0x2000
	s_waitcnt lgkmcnt(4)
	s_waitcnt vmcnt(2)
	v_mfma_f32_32x32x16_bf16 v[34:49], v[64:67], v[122:125], v[34:49]
	s_waitcnt lgkmcnt(2)
	v_mfma_f32_32x32x16_bf16 v[18:33], v[68:71], v[122:125], v[18:33]
	s_waitcnt vmcnt(1)
	v_mfma_f32_32x32x16_bf16 v[34:49], v[72:75], v[118:121], v[34:49]
	s_waitcnt lgkmcnt(0)
	v_mfma_f32_32x32x16_bf16 v[18:33], v[76:79], v[118:121], v[18:33]
	v_add_u32_e32 v64, 64, v50
	v_add_u32_e32 v68, 0x60, v50
	v_mad_i64_i32 v[66:67], s[4:5], v64, s55, v[54:55]
	v_mad_i64_i32 v[54:55], s[4:5], v68, s55, v[54:55]
	v_ashrrev_i32_e32 v65, 31, v64
	v_ashrrev_i32_e32 v69, 31, v68
	s_waitcnt vmcnt(0)
; #define SWAIT() do { if constexpr (SDEPTH == 2) { if constexpr (NDQ == 4) asm volatile("s_waitcnt vmcnt(3)" ::: "memory"); else if constexpr (NDQ == 8) asm volatile("s_waitcnt vmcnt(4)" ::: "memory"); else asm volatile("s_waitcnt vmcnt(5)" ::: "memory"); } \
;     else asm volatile("s_waitcnt vmcnt(0)" ::: "memory"); } while (0)
; #define BIASADD(P0, P1, kt0) do { if constexpr (BIAS) { const int dlo_ = (kt0) - q0 - 255, dhi_ = (kt0) + 63 - q0; \
;     if (!(dlo_ >= 1024) && !(dhi_ <= -1024)) { const float* tb_ = tbl_l + ((kt0) - qlane + TOFF + 4 * hi); \
;       _Pragma("unroll") for (int r = 0; r < 16; ++r) { P0[r] += tb_[(r & 3) + 8 * (r >> 2)]; P1[r] += tb_[32 + (r & 3) + 8 * (r >> 2)]; } } } } while (0)
; template <bool FIRST>
; __device__ __forceinline__ void partialSM(f32x16& p0, f32x16& p1, float& mC, float& alpha) {
;   float mx_[4] = {p0[0], p0[1], p0[2], p0[3]};
; #pragma unroll
;   for (int r = 4; r < 16; ++r) mx_[r & 3] = fmaxf(mx_[r & 3], p0[r]);
; #pragma unroll
;   for (int r = 0; r < 16; ++r) mx_[r & 3] = fmaxf(mx_[r & 3], p1[r]);
;   float pmax = fmaxf(fmaxf(mx_[0], mx_[1]), fmaxf(mx_[2], mx_[3]));
;   { auto rr = __builtin_amdgcn_permlane32_swap(__float_as_uint(pmax), __float_as_uint(pmax), false, false);
;     pmax = fmaxf(__uint_as_float(rr[0]), __uint_as_float(rr[1])); }
;   if (!FIRST && __builtin_expect(__all(pmax <= THR2), 1)) { alpha = 1.f; }
;   else { const float delta = FIRST ? fmaxf(pmax, -200.f) : fmaxf(pmax, 0.f); alpha = FIRST ? 1.f : __builtin_amdgcn_exp2f(-delta); mC += delta;
; #pragma unroll
;     for (int r = 0; r < 16; ++r) p0[r] -= delta;
; #pragma unroll
;     for (int r = 0; r < 16; ++r) p1[r] -= delta; }
; #pragma unroll
;   for (int r = 0; r < 16; ++r) p0[r] = __builtin_amdgcn_exp2f(p0[r]);
; }
;     ...
;   NEGM_UPD(kbeg); QKT(pA0, pA1, 0); BIASADD(pA0, pA1, kbeg); partialSM<true>(pA0, pA1, mC, alA);
;   if constexpr (SLICED) {
; #pragma unroll
;     for (int r = 0; r < 16; ++r) pA1[r] = __builtin_amdgcn_exp2f(pA1[r]); }
;   SLOAD(SO, kbeg + KVBLK); if constexpr (SDEPTH == 2) { if (2 < NT) SLOAD(SE, kbeg + 2 * KVBLK); }
;   SWAIT(); SWRITE(1, SO); __syncthreads();
	v_mfma_f32_32x32x16_bf16 v[34:49], v[56:59], v[114:117], v[34:49]
	v_lshl_add_u64 v[56:57], v[66:67], 0, v[0:1]
	v_lshl_add_u64 v[58:59], v[54:55], 0, v[0:1]
	global_load_dwordx4 v[54:57], v[56:57], off
	s_nop 0
	global_load_dwordx4 v[82:85], v[58:59], off
	v_lshlrev_b64 v[58:59], 9, v[64:65]
	v_lshl_add_u64 v[58:59], s[50:51], 0, v[58:59]
	v_lshl_add_u64 v[58:59], v[58:59], 0, v[0:1]
	s_mov_b32 s4, 0xc3480000
	v_mfma_f32_32x32x16_bf16 v[18:33], v[60:63], v[114:117], v[18:33]
	v_lshlrev_b64 v[60:61], 9, v[68:69]
	v_lshl_add_u64 v[60:61], s[50:51], 0, v[60:61]
	v_lshl_add_u64 v[62:63], v[60:61], 0, v[0:1]
	global_load_dwordx4 v[58:61], v[58:59], off
	s_nop 0
	global_load_dwordx4 v[62:65], v[62:63], off
	v_max_f32_e32 v66, v38, v38
	v_max_f32_e32 v0, v34, v34
	v_max_f32_e32 v0, v0, v66
	v_max_f32_e32 v66, v39, v39
	v_max_f32_e32 v67, v35, v35
	v_max_f32_e32 v66, v67, v66
	v_max_f32_e32 v67, v41, v41
	v_max_f32_e32 v68, v37, v37
	v_max_f32_e32 v67, v68, v67
	v_max3_f32 v68, v36, v40, v44
	v_max3_f32 v67, v67, v45, v49
	v_max3_f32 v0, v0, v42, v46
	v_max3_f32 v66, v66, v43, v47
	v_max3_f32 v68, v68, v48, v20
	v_max3_f32 v67, v67, v21, v25
	v_max3_f32 v0, v0, v18, v22
	v_max3_f32 v66, v66, v19, v23
	v_max3_f32 v68, v68, v24, v28
	v_max3_f32 v67, v67, v29, v33
	v_max3_f32 v0, v0, v26, v30
	v_max3_f32 v66, v66, v27, v31
	v_max3_f32 v67, v68, v32, v67
	v_max3_f32 v0, v0, v66, v67
	v_mov_b32_e32 v66, v0
	s_nop 1
	v_permlane32_swap_b32_e32 v0, v66
	v_max3_f32 v0, v0, v66, s4
	s_addk_i32 s6, 0x4000
	v_sub_f32_e32 v34, v34, v0
	v_sub_f32_e32 v35, v35, v0
	v_sub_f32_e32 v36, v36, v0
	v_sub_f32_e32 v37, v37, v0
	v_sub_f32_e32 v38, v38, v0
	v_sub_f32_e32 v39, v39, v0
	v_sub_f32_e32 v40, v40, v0
	v_sub_f32_e32 v41, v41, v0
	v_sub_f32_e32 v42, v42, v0
	v_sub_f32_e32 v43, v43, v0
	v_sub_f32_e32 v44, v44, v0
	v_sub_f32_e32 v45, v45, v0
	v_sub_f32_e32 v46, v46, v0
	v_sub_f32_e32 v47, v47, v0
	v_sub_f32_e32 v48, v48, v0
	v_sub_f32_e32 v49, v49, v0
	v_add_u32_e32 v198, s6, v86
	s_add_u32 s6, s42, s64
	v_exp_f32_e32 v146, v34
	v_exp_f32_e32 v161, v35
	v_exp_f32_e32 v147, v36
	v_exp_f32_e32 v160, v37
	v_exp_f32_e32 v148, v38
	v_exp_f32_e32 v159, v39
	v_exp_f32_e32 v149, v40
	v_exp_f32_e32 v158, v41
	v_exp_f32_e32 v150, v42
	v_exp_f32_e32 v157, v43
	v_exp_f32_e32 v151, v44
	v_exp_f32_e32 v156, v45
	v_exp_f32_e32 v152, v46
	v_exp_f32_e32 v155, v47
	v_exp_f32_e32 v153, v48
	v_exp_f32_e32 v154, v49
	s_addc_u32 s7, s43, 0
	v_sub_f32_e32 v67, v19, v0
	v_sub_f32_e32 v66, v18, v0
	s_waitcnt vmcnt(0)
	v_mov_b64_e32 v[18:19], s[6:7]
	v_sub_f32_e32 v81, v33, v0
	v_sub_f32_e32 v80, v32, v0
	v_sub_f32_e32 v79, v31, v0
	v_sub_f32_e32 v78, v30, v0
	v_sub_f32_e32 v77, v29, v0
	v_sub_f32_e32 v76, v28, v0
	v_sub_f32_e32 v75, v27, v0
	v_sub_f32_e32 v74, v26, v0
	v_sub_f32_e32 v73, v25, v0
	v_sub_f32_e32 v72, v24, v0
	v_sub_f32_e32 v71, v23, v0
	v_sub_f32_e32 v70, v22, v0
	v_sub_f32_e32 v69, v21, v0
	v_sub_f32_e32 v68, v20, v0
	s_waitcnt vmcnt(3)
	ds_write_b128 v201, v[54:57] offset:16384
	s_waitcnt vmcnt(2)
	ds_write_b128 v207, v[82:85] offset:16384
	s_waitcnt vmcnt(1)
	ds_write_b128 v208, v[58:61] offset:49152
	s_waitcnt vmcnt(0)
	ds_write_b128 v209, v[62:65] offset:49152
	v_add_u32_e32 v224, 0x4000, v200
	v_cmp_gt_u32_e64 s[4:5], 32, v51
	v_lshl_add_u64 v[184:185], s[6:7], 0, v[52:53]
	v_mad_i64_i32 v[186:187], s[6:7], v50, s55, v[18:19]
	v_add_co_u32_e32 v186, vcc, 0xfff60000, v186
	s_nop 1
	v_addc_co_u32_e32 v187, vcc, -1, v187, vcc
	v_mov_b32_e32 v232, 0
	v_mov_b64_e32 v[64:65], v[16:17]
	v_mov_b64_e32 v[48:49], v[16:17]
	v_mov_b64_e32 v[32:33], v[16:17]
	v_add_f32_e32 v227, 0, v0
	v_xor_b32_e32 v223, 32, v224
	v_xor_b32_e32 v222, 64, v224
	v_xor_b32_e32 v221, 0x60, v224
	v_xor_b32_e32 v220, 0x80, v224
	v_xor_b32_e32 v219, 0xa0, v224
	v_xor_b32_e32 v218, 0xc0, v224
	v_xor_b32_e32 v217, 0xe0, v224
	v_lshl_add_u32 v183, v178, 2, v179
	v_add_u32_e32 v181, v179, v182
	v_lshlrev_b32_e32 v0, 4, v87
	v_mov_b32_e32 v225, 1.0
	v_mov_b64_e32 v[62:63], v[14:15]
	v_mov_b64_e32 v[60:61], v[12:13]
	v_mov_b64_e32 v[58:59], v[10:11]
	v_mov_b64_e32 v[56:57], v[8:9]
	v_mov_b64_e32 v[54:55], v[6:7]
	v_mov_b64_e32 v[52:53], v[4:5]
	v_mov_b64_e32 v[50:51], v[2:3]
	v_mov_b64_e32 v[46:47], v[14:15]
	v_mov_b64_e32 v[44:45], v[12:13]
	v_mov_b64_e32 v[42:43], v[10:11]
	v_mov_b64_e32 v[40:41], v[8:9]
	v_mov_b64_e32 v[38:39], v[6:7]
	v_mov_b64_e32 v[36:37], v[4:5]
	v_mov_b64_e32 v[34:35], v[2:3]
	v_mov_b64_e32 v[30:31], v[14:15]
	v_mov_b64_e32 v[28:29], v[12:13]
	v_mov_b64_e32 v[26:27], v[10:11]
	v_mov_b64_e32 v[24:25], v[8:9]
	v_mov_b64_e32 v[22:23], v[6:7]
	v_mov_b64_e32 v[20:21], v[4:5]
	v_mov_b64_e32 v[18:19], v[2:3]
	v_mov_b32_e32 v197, 0
	v_mov_b32_e32 v82, 0
	v_mov_b32_e32 v83, v232
	v_mov_b32_e32 v84, v232
	v_mov_b32_e32 v85, v232
	v_mov_b32_e32 v86, v232
	v_mov_b32_e32 v87, v232
	v_mov_b32_e32 v88, v232
	v_mov_b32_e32 v89, v232
	v_mov_b32_e32 v90, v232
	v_mov_b32_e32 v91, v232
	v_mov_b32_e32 v92, v232
	v_mov_b32_e32 v93, v232
	v_mov_b32_e32 v94, v232
	v_mov_b32_e32 v95, v232
	v_mov_b32_e32 v96, v232
	v_mov_b32_e32 v97, v232
	s_waitcnt lgkmcnt(0)
	s_barrier

; __device__ __forceinline__ void pv_d0(f32x16* o, int vb, bf16x8 pa0, bf16x8 pa1, bf16x8 pa2, bf16x8 pa3) {
;     ...
;   const s16x4 l0 = tr_read<v_rd_off(0, 0, 0)>(vb), h0 = tr_read<v_rd_off(0, 0, 1)>(vb);
;   const s16x4 l1 = tr_read<v_rd_off(0, 1, 0)>(vb), h1 = tr_read<v_rd_off(0, 1, 1)>(vb);
;   const s16x4 l2 = tr_read<v_rd_off(0, 2, 0)>(vb), h2 = tr_read<v_rd_off(0, 2, 1)>(vb);
;   const s16x4 l3 = tr_read<v_rd_off(0, 3, 0)>(vb), h3 = tr_read<v_rd_off(0, 3, 1)>(vb);
;   const s16x4 l4 = tr_read<v_rd_off(1, 0, 0)>(vb), h4 = tr_read<v_rd_off(1, 0, 1)>(vb);
;   asm volatile("s_waitcnt lgkmcnt(8)" ::: "memory"); SBAR();
;   o[0] = __builtin_amdgcn_mfma_f32_32x32x16_bf16(pa0, PK(l0, h0), o[0], 0, 0, 0);
;   const s16x4 l5 = tr_read<v_rd_off(1, 1, 0)>(vb), h5 = tr_read<v_rd_off(1, 1, 1)>(vb);
;   asm volatile("s_waitcnt lgkmcnt(8)" ::: "memory"); SBAR();
;   o[0] = __builtin_amdgcn_mfma_f32_32x32x16_bf16(pa1, PK(l1, h1), o[0], 0, 0, 0);
;   const s16x4 l6 = tr_read<v_rd_off(1, 2, 0)>(vb), h6 = tr_read<v_rd_off(1, 2, 1)>(vb);
;   asm volatile("s_waitcnt lgkmcnt(8)" ::: "memory"); SBAR();
;   o[0] = __builtin_amdgcn_mfma_f32_32x32x16_bf16(pa2, PK(l2, h2), o[0], 0, 0, 0);
;   const s16x4 l7 = tr_read<v_rd_off(1, 3, 0)>(vb), h7 = tr_read<v_rd_off(1, 3, 1)>(vb);
;   asm volatile("s_waitcnt lgkmcnt(8)" ::: "memory"); SBAR();
;   o[0] = __builtin_amdgcn_mfma_f32_32x32x16_bf16(pa3, PK(l3, h3), o[0], 0, 0, 0);
;   const s16x4 l8 = tr_read<v_rd_off(2, 0, 0)>(vb), h8 = tr_read<v_rd_off(2, 0, 1)>(vb);
;   asm volatile("s_waitcnt lgkmcnt(8)" ::: "memory"); SBAR();
;   o[1] = __builtin_amdgcn_mfma_f32_32x32x16_bf16(pa0, PK(l4, h4), o[1], 0, 0, 0);
;   const s16x4 l9 = tr_read<v_rd_off(2, 1, 0)>(vb), h9 = tr_read<v_rd_off(2, 1, 1)>(vb);
;   asm volatile("s_waitcnt lgkmcnt(8)" ::: "memory"); SBAR();
;   o[1] = __builtin_amdgcn_mfma_f32_32x32x16_bf16(pa1, PK(l5, h5), o[1], 0, 0, 0);
;   const s16x4 l10 = tr_read<v_rd_off(2, 2, 0)>(vb), h10 = tr_read<v_rd_off(2, 2, 1)>(vb);
;   asm volatile("s_waitcnt lgkmcnt(8)" ::: "memory"); SBAR();
;   o[1] = __builtin_amdgcn_mfma_f32_32x32x16_bf16(pa2, PK(l6, h6), o[1], 0, 0, 0);
;   const s16x4 l11 = tr_read<v_rd_off(2, 3, 0)>(vb), h11 = tr_read<v_rd_off(2, 3, 1)>(vb);
;   asm volatile("s_waitcnt lgkmcnt(8)" ::: "memory"); SBAR();
;   o[1] = __builtin_amdgcn_mfma_f32_32x32x16_bf16(pa3, PK(l7, h7), o[1], 0, 0, 0);
.LBB0_423:
	v_lshl_add_u64 v[188:189], v[186:187], 0, v[0:1]
	v_add_co_u32_e32 v162, vcc, s78, v188
	v_lshl_add_u64 v[190:191], v[184:185], 0, v[0:1]
	s_nop 0
	v_addc_co_u32_e32 v163, vcc, 0, v189, vcc
	v_add_co_u32_e32 v166, vcc, s79, v188
	s_nop 1
	v_addc_co_u32_e32 v167, vcc, 0, v189, vcc
	v_add_co_u32_e32 v170, vcc, s70, v190
	global_load_dwordx4 v[162:165], v[162:163], off offset:2176
	s_nop 0
	global_load_dwordx4 v[166:169], v[166:167], off offset:2176
	v_addc_co_u32_e32 v171, vcc, 0, v191, vcc
	v_add_co_u32_e32 v174, vcc, s71, v190
	s_nop 1
	v_addc_co_u32_e32 v175, vcc, 0, v191, vcc
	global_load_dwordx4 v[170:173], v[170:171], off
	s_nop 0
	global_load_dwordx4 v[174:177], v[174:175], off
	ds_read_b64_tr_b16 v[192:193], v199 offset:0
	ds_read_b64_tr_b16 v[194:195], v199 offset:0x800
	ds_read_b64_tr_b16 v[234:235], v199 offset:0x1000
	ds_read_b64_tr_b16 v[236:237], v199 offset:0x1800
	ds_read_b64_tr_b16 v[238:239], v199 offset:0x2000
	ds_read_b64_tr_b16 v[240:241], v199 offset:0x2800
	ds_read_b64_tr_b16 v[242:243], v199 offset:0x3000
	ds_read_b64_tr_b16 v[244:245], v199 offset:0x3800
	ds_read_b64_tr_b16 v[246:247], v199 offset:0x200
	ds_read_b64_tr_b16 v[248:249], v199 offset:0xa00
	s_waitcnt lgkmcnt(8)
	s_nop 0
	v_mfma_f32_32x32x16_bf16 v[2:17], v[146:149], v[192:195], v[2:17]
	ds_read_b64_tr_b16 v[192:193], v199 offset:0x1200
	ds_read_b64_tr_b16 v[194:195], v199 offset:0x1a00
	s_waitcnt lgkmcnt(8)
	v_mfma_f32_32x32x16_bf16 v[2:17], v[150:153], v[234:237], v[2:17]
	ds_read_b64_tr_b16 v[234:235], v199 offset:0x2200
	ds_read_b64_tr_b16 v[236:237], v199 offset:0x2a00
	s_waitcnt lgkmcnt(8)
	v_mfma_f32_32x32x16_bf16 v[2:17], v[158:161], v[238:241], v[2:17]
	ds_read_b64_tr_b16 v[238:239], v199 offset:0x3200
	ds_read_b64_tr_b16 v[240:241], v199 offset:0x3a00
	s_waitcnt lgkmcnt(8)
	v_mfma_f32_32x32x16_bf16 v[2:17], v[154:157], v[242:245], v[2:17]
	ds_read_b64_tr_b16 v[242:243], v199 offset:0x400
	ds_read_b64_tr_b16 v[244:245], v199 offset:0xc00
	s_waitcnt lgkmcnt(8)
	v_mfma_f32_32x32x16_bf16 v[50:65], v[146:149], v[246:249], v[50:65]
	ds_read_b64_tr_b16 v[246:247], v199 offset:0x1400
	ds_read_b64_tr_b16 v[248:249], v199 offset:0x1c00
	s_waitcnt lgkmcnt(8)
	v_mfma_f32_32x32x16_bf16 v[50:65], v[150:153], v[192:195], v[50:65]
	ds_read_b64_tr_b16 v[192:193], v199 offset:0x2400
	ds_read_b64_tr_b16 v[194:195], v199 offset:0x2c00
	s_waitcnt lgkmcnt(8)
	v_mfma_f32_32x32x16_bf16 v[50:65], v[158:161], v[234:237], v[50:65]
	ds_read_b64_tr_b16 v[234:235], v199 offset:0x3400
	ds_read_b64_tr_b16 v[236:237], v199 offset:0x3c00
	s_waitcnt lgkmcnt(8)
	v_mfma_f32_32x32x16_bf16 v[50:65], v[154:157], v[238:241], v[50:65]
	ds_read_b64_tr_b16 v[238:239], v199 offset:0x600
	ds_read_b64_tr_b16 v[240:241], v199 offset:0xe00
	s_waitcnt lgkmcnt(8)
	v_mfma_f32_32x32x16_bf16 v[34:49], v[146:149], v[242:245], v[34:49]
	ds_read_b64_tr_b16 v[242:243], v199 offset:0x1600
	ds_read_b64_tr_b16 v[244:245], v199 offset:0x1e00
	s_waitcnt lgkmcnt(8)
	v_mfma_f32_32x32x16_bf16 v[34:49], v[150:153], v[246:249], v[34:49]
	ds_read_b64_tr_b16 v[246:247], v199 offset:0x2600
	ds_read_b64_tr_b16 v[248:249], v199 offset:0x2e00
	s_waitcnt lgkmcnt(8)
	v_mfma_f32_32x32x16_bf16 v[34:49], v[158:161], v[192:195], v[34:49]
	ds_read_b64_tr_b16 v[192:193], v199 offset:0x3600
	ds_read_b64_tr_b16 v[194:195], v199 offset:0x3e00
	s_waitcnt lgkmcnt(8)
	v_mfma_f32_32x32x16_bf16 v[34:49], v[154:157], v[234:237], v[34:49]
	s_waitcnt lgkmcnt(6)
	v_mfma_f32_32x32x16_bf16 v[18:33], v[146:149], v[238:241], v[18:33]
	s_waitcnt lgkmcnt(4)
	v_mfma_f32_32x32x16_bf16 v[18:33], v[150:153], v[242:245], v[18:33]
	s_waitcnt lgkmcnt(2)
	v_mfma_f32_32x32x16_bf16 v[18:33], v[158:161], v[246:249], v[18:33]
	s_waitcnt lgkmcnt(0)
	v_mfma_f32_32x32x16_bf16 v[18:33], v[154:157], v[192:195], v[18:33]
	s_waitcnt vmcnt(0)
	v_cmp_gt_f32_e32 vcc, 1.0, v230
	s_waitcnt vmcnt(3)
	ds_write_b128 v201, v[162:165] offset:16384
	s_waitcnt vmcnt(2)
	ds_write_b128 v207, v[166:169] offset:16384
	s_waitcnt vmcnt(1)
	ds_write_b128 v208, v[170:173] offset:32768
	s_waitcnt vmcnt(0)
	ds_write_b128 v209, v[174:177] offset:32768
	s_cbranch_vccz .LBB0_427
	s_and_saveexec_b64 s[10:11], s[4:5]
	ds_write_b32 v183, v230 offset:128
	s_or_b64 exec, exec, s[10:11]
	s_waitcnt lgkmcnt(0)
	ds_read_b128 v[146:149], v181 offset:224
	ds_read_b128 v[150:153], v181 offset:192
	ds_read_b128 v[154:157], v181 offset:160
	ds_read_b128 v[158:161], v181 offset:128
	s_waitcnt lgkmcnt(3)
	v_pk_mul_f32 v[16:17], v[16:17], v[148:149]
	s_waitcnt lgkmcnt(2)
	v_pk_mul_f32 v[12:13], v[12:13], v[152:153]
	s_waitcnt lgkmcnt(1)
	v_pk_mul_f32 v[8:9], v[8:9], v[156:157]
	s_waitcnt lgkmcnt(0)
	v_pk_mul_f32 v[4:5], v[4:5], v[160:161]
	v_pk_mul_f32 v[14:15], v[14:15], v[146:147]
	v_pk_mul_f32 v[10:11], v[10:11], v[150:151]
	v_pk_mul_f32 v[6:7], v[6:7], v[154:155]
	v_pk_mul_f32 v[2:3], v[2:3], v[158:159]
	v_pk_mul_f32 v[64:65], v[64:65], v[148:149]
	v_pk_mul_f32 v[60:61], v[60:61], v[152:153]
	v_pk_mul_f32 v[56:57], v[56:57], v[156:157]
	v_pk_mul_f32 v[52:53], v[52:53], v[160:161]
	v_pk_mul_f32 v[62:63], v[62:63], v[146:147]
	v_pk_mul_f32 v[58:59], v[58:59], v[150:151]
	v_pk_mul_f32 v[54:55], v[54:55], v[154:155]
	v_pk_mul_f32 v[50:51], v[50:51], v[158:159]
	v_pk_mul_f32 v[48:49], v[48:49], v[148:149]
	v_pk_mul_f32 v[44:45], v[44:45], v[152:153]
	v_pk_mul_f32 v[40:41], v[40:41], v[156:157]
	v_pk_mul_f32 v[36:37], v[36:37], v[160:161]
	v_pk_mul_f32 v[46:47], v[46:47], v[146:147]
	v_pk_mul_f32 v[42:43], v[42:43], v[150:151]
	v_pk_mul_f32 v[38:39], v[38:39], v[154:155]
	v_pk_mul_f32 v[34:35], v[34:35], v[158:159]
	v_pk_mul_f32 v[32:33], v[32:33], v[148:149]
	v_pk_mul_f32 v[28:29], v[28:29], v[152:153]
	v_pk_mul_f32 v[24:25], v[24:25], v[156:157]
	v_pk_mul_f32 v[20:21], v[20:21], v[160:161]
	v_pk_mul_f32 v[30:31], v[30:31], v[146:147]
	v_pk_mul_f32 v[26:27], v[26:27], v[150:151]
	v_pk_mul_f32 v[22:23], v[22:23], v[154:155]
	v_pk_mul_f32 v[18:19], v[18:19], v[158:159]

; __device__ __forceinline__ void pv_d0(f32x16* o, int vb, bf16x8 pa0, bf16x8 pa1, bf16x8 pa2, bf16x8 pa3) {
;     ...
;   const s16x4 l0 = tr_read<v_rd_off(0, 0, 0)>(vb), h0 = tr_read<v_rd_off(0, 0, 1)>(vb);
;   const s16x4 l1 = tr_read<v_rd_off(0, 1, 0)>(vb), h1 = tr_read<v_rd_off(0, 1, 1)>(vb);
;   const s16x4 l2 = tr_read<v_rd_off(0, 2, 0)>(vb), h2 = tr_read<v_rd_off(0, 2, 1)>(vb);
;   const s16x4 l3 = tr_read<v_rd_off(0, 3, 0)>(vb), h3 = tr_read<v_rd_off(0, 3, 1)>(vb);
;   const s16x4 l4 = tr_read<v_rd_off(1, 0, 0)>(vb), h4 = tr_read<v_rd_off(1, 0, 1)>(vb);
;   asm volatile("s_waitcnt lgkmcnt(8)" ::: "memory"); SBAR();
;   o[0] = __builtin_amdgcn_mfma_f32_32x32x16_bf16(pa0, PK(l0, h0), o[0], 0, 0, 0);
;   const s16x4 l5 = tr_read<v_rd_off(1, 1, 0)>(vb), h5 = tr_read<v_rd_off(1, 1, 1)>(vb);
;   asm volatile("s_waitcnt lgkmcnt(8)" ::: "memory"); SBAR();
;   o[0] = __builtin_amdgcn_mfma_f32_32x32x16_bf16(pa1, PK(l1, h1), o[0], 0, 0, 0);
;   const s16x4 l6 = tr_read<v_rd_off(1, 2, 0)>(vb), h6 = tr_read<v_rd_off(1, 2, 1)>(vb);
;   asm volatile("s_waitcnt lgkmcnt(8)" ::: "memory"); SBAR();
;   o[0] = __builtin_amdgcn_mfma_f32_32x32x16_bf16(pa2, PK(l2, h2), o[0], 0, 0, 0);
;   const s16x4 l7 = tr_read<v_rd_off(1, 3, 0)>(vb), h7 = tr_read<v_rd_off(1, 3, 1)>(vb);
;   asm volatile("s_waitcnt lgkmcnt(8)" ::: "memory"); SBAR();
;   o[0] = __builtin_amdgcn_mfma_f32_32x32x16_bf16(pa3, PK(l3, h3), o[0], 0, 0, 0);
;   const s16x4 l8 = tr_read<v_rd_off(2, 0, 0)>(vb), h8 = tr_read<v_rd_off(2, 0, 1)>(vb);
;   asm volatile("s_waitcnt lgkmcnt(8)" ::: "memory"); SBAR();
;   o[1] = __builtin_amdgcn_mfma_f32_32x32x16_bf16(pa0, PK(l4, h4), o[1], 0, 0, 0);
;   const s16x4 l9 = tr_read<v_rd_off(2, 1, 0)>(vb), h9 = tr_read<v_rd_off(2, 1, 1)>(vb);
;   asm volatile("s_waitcnt lgkmcnt(8)" ::: "memory"); SBAR();
;   o[1] = __builtin_amdgcn_mfma_f32_32x32x16_bf16(pa1, PK(l5, h5), o[1], 0, 0, 0);
;   const s16x4 l10 = tr_read<v_rd_off(2, 2, 0)>(vb), h10 = tr_read<v_rd_off(2, 2, 1)>(vb);
;   asm volatile("s_waitcnt lgkmcnt(8)" ::: "memory"); SBAR();
;   o[1] = __builtin_amdgcn_mfma_f32_32x32x16_bf16(pa2, PK(l6, h6), o[1], 0, 0, 0);
;   const s16x4 l11 = tr_read<v_rd_off(2, 3, 0)>(vb), h11 = tr_read<v_rd_off(2, 3, 1)>(vb);
;   asm volatile("s_waitcnt lgkmcnt(8)" ::: "memory"); SBAR();
;   o[1] = __builtin_amdgcn_mfma_f32_32x32x16_bf16(pa3, PK(l7, h7), o[1], 0, 0, 0);
.LBB0_429:
	v_add_co_u32_e32 v162, vcc, s72, v188
	s_nop 1
	v_addc_co_u32_e32 v163, vcc, 0, v189, vcc
	v_add_co_u32_e32 v166, vcc, s73, v188
	s_nop 1
	v_addc_co_u32_e32 v167, vcc, 0, v189, vcc
	v_add_co_u32_e32 v170, vcc, s33, v190
	global_load_dwordx4 v[162:165], v[162:163], off offset:2176
	s_nop 0
	global_load_dwordx4 v[166:169], v[166:167], off offset:2176
	v_addc_co_u32_e32 v171, vcc, 0, v191, vcc
	v_add_co_u32_e32 v174, vcc, s52, v190
	s_nop 1
	v_addc_co_u32_e32 v175, vcc, 0, v191, vcc
	global_load_dwordx4 v[170:173], v[170:171], off
	s_nop 0
	global_load_dwordx4 v[174:177], v[174:175], off
	ds_read_b64_tr_b16 v[188:189], v198 offset:0
	ds_read_b64_tr_b16 v[190:191], v198 offset:0x800
	ds_read_b64_tr_b16 v[192:193], v198 offset:0x1000
	ds_read_b64_tr_b16 v[194:195], v198 offset:0x1800
	ds_read_b64_tr_b16 v[236:237], v198 offset:0x2000
	ds_read_b64_tr_b16 v[238:239], v198 offset:0x2800
	ds_read_b64_tr_b16 v[240:241], v198 offset:0x3000
	ds_read_b64_tr_b16 v[242:243], v198 offset:0x3800
	ds_read_b64_tr_b16 v[244:245], v198 offset:0x200
	ds_read_b64_tr_b16 v[246:247], v198 offset:0xa00
	s_waitcnt lgkmcnt(8)
	s_nop 0
	v_mfma_f32_32x32x16_bf16 v[2:17], v[146:149], v[188:191], v[2:17]
	ds_read_b64_tr_b16 v[188:189], v198 offset:0x1200
	ds_read_b64_tr_b16 v[190:191], v198 offset:0x1a00
	s_waitcnt lgkmcnt(8)
	v_mfma_f32_32x32x16_bf16 v[2:17], v[150:153], v[192:195], v[2:17]
	ds_read_b64_tr_b16 v[192:193], v198 offset:0x2200
	ds_read_b64_tr_b16 v[194:195], v198 offset:0x2a00
	s_waitcnt lgkmcnt(8)
	v_mfma_f32_32x32x16_bf16 v[2:17], v[158:161], v[236:239], v[2:17]
	ds_read_b64_tr_b16 v[236:237], v198 offset:0x3200
	ds_read_b64_tr_b16 v[238:239], v198 offset:0x3a00
	s_waitcnt lgkmcnt(8)
	v_mfma_f32_32x32x16_bf16 v[2:17], v[154:157], v[240:243], v[2:17]
	ds_read_b64_tr_b16 v[240:241], v198 offset:0x400
	ds_read_b64_tr_b16 v[242:243], v198 offset:0xc00
	s_waitcnt lgkmcnt(8)
	v_mfma_f32_32x32x16_bf16 v[50:65], v[146:149], v[244:247], v[50:65]
	ds_read_b64_tr_b16 v[244:245], v198 offset:0x1400
	ds_read_b64_tr_b16 v[246:247], v198 offset:0x1c00
	s_waitcnt lgkmcnt(8)
	v_mfma_f32_32x32x16_bf16 v[50:65], v[150:153], v[188:191], v[50:65]
	ds_read_b64_tr_b16 v[188:189], v198 offset:0x2400
	ds_read_b64_tr_b16 v[190:191], v198 offset:0x2c00
	s_waitcnt lgkmcnt(8)
	v_mfma_f32_32x32x16_bf16 v[50:65], v[158:161], v[192:195], v[50:65]
	ds_read_b64_tr_b16 v[192:193], v198 offset:0x3400
	ds_read_b64_tr_b16 v[194:195], v198 offset:0x3c00
	s_waitcnt lgkmcnt(8)
	v_mfma_f32_32x32x16_bf16 v[50:65], v[154:157], v[236:239], v[50:65]
	ds_read_b64_tr_b16 v[236:237], v198 offset:0x600
	ds_read_b64_tr_b16 v[238:239], v198 offset:0xe00
	s_waitcnt lgkmcnt(8)
	v_mfma_f32_32x32x16_bf16 v[34:49], v[146:149], v[240:243], v[34:49]
	ds_read_b64_tr_b16 v[240:241], v198 offset:0x1600
	ds_read_b64_tr_b16 v[242:243], v198 offset:0x1e00
	s_waitcnt lgkmcnt(8)
	v_mfma_f32_32x32x16_bf16 v[34:49], v[150:153], v[244:247], v[34:49]
	ds_read_b64_tr_b16 v[244:245], v198 offset:0x2600
	ds_read_b64_tr_b16 v[246:247], v198 offset:0x2e00
	s_waitcnt lgkmcnt(8)
	v_mfma_f32_32x32x16_bf16 v[34:49], v[158:161], v[188:191], v[34:49]
	ds_read_b64_tr_b16 v[188:189], v198 offset:0x3600
	ds_read_b64_tr_b16 v[190:191], v198 offset:0x3e00
	s_waitcnt lgkmcnt(8)
	v_mfma_f32_32x32x16_bf16 v[34:49], v[154:157], v[192:195], v[34:49]
	s_waitcnt lgkmcnt(6)
	v_mfma_f32_32x32x16_bf16 v[18:33], v[146:149], v[236:239], v[18:33]
	s_waitcnt lgkmcnt(4)
	v_mfma_f32_32x32x16_bf16 v[18:33], v[150:153], v[240:243], v[18:33]
	s_waitcnt lgkmcnt(2)
	v_mfma_f32_32x32x16_bf16 v[18:33], v[158:161], v[244:247], v[18:33]
	s_waitcnt lgkmcnt(0)
	v_mfma_f32_32x32x16_bf16 v[18:33], v[154:157], v[188:191], v[18:33]
	s_waitcnt vmcnt(0)
	v_cmp_gt_f32_e32 vcc, 1.0, v226
	s_waitcnt vmcnt(3)
	ds_write_b128 v201, v[162:165]
	s_waitcnt vmcnt(2)
	ds_write_b128 v207, v[166:169]
	s_waitcnt vmcnt(1)
	ds_write_b128 v208, v[170:173] offset:49152
	s_waitcnt vmcnt(0)
	ds_write_b128 v209, v[174:177] offset:49152
	s_cbranch_vccz .LBB0_433
	s_and_saveexec_b64 s[10:11], s[4:5]
	ds_write_b32 v183, v226 offset:128
	s_or_b64 exec, exec, s[10:11]
	s_waitcnt lgkmcnt(0)
	ds_read_b128 v[146:149], v181 offset:224
	ds_read_b128 v[150:153], v181 offset:192
	ds_read_b128 v[154:157], v181 offset:160
	ds_read_b128 v[158:161], v181 offset:128
	s_waitcnt lgkmcnt(3)
	v_pk_mul_f32 v[16:17], v[16:17], v[148:149]
	s_waitcnt lgkmcnt(2)
	v_pk_mul_f32 v[12:13], v[12:13], v[152:153]
	s_waitcnt lgkmcnt(1)
	v_pk_mul_f32 v[8:9], v[8:9], v[156:157]
	s_waitcnt lgkmcnt(0)
	v_pk_mul_f32 v[4:5], v[4:5], v[160:161]
	v_pk_mul_f32 v[14:15], v[14:15], v[146:147]
	v_pk_mul_f32 v[10:11], v[10:11], v[150:151]
	v_pk_mul_f32 v[6:7], v[6:7], v[154:155]
	v_pk_mul_f32 v[2:3], v[2:3], v[158:159]
	v_pk_mul_f32 v[64:65], v[64:65], v[148:149]
	v_pk_mul_f32 v[60:61], v[60:61], v[152:153]
	v_pk_mul_f32 v[56:57], v[56:57], v[156:157]
	v_pk_mul_f32 v[52:53], v[52:53], v[160:161]
	v_pk_mul_f32 v[62:63], v[62:63], v[146:147]
	v_pk_mul_f32 v[58:59], v[58:59], v[150:151]
	v_pk_mul_f32 v[54:55], v[54:55], v[154:155]
	v_pk_mul_f32 v[50:51], v[50:51], v[158:159]
	v_pk_mul_f32 v[48:49], v[48:49], v[148:149]
	v_pk_mul_f32 v[44:45], v[44:45], v[152:153]
	v_pk_mul_f32 v[40:41], v[40:41], v[156:157]
	v_pk_mul_f32 v[36:37], v[36:37], v[160:161]
	v_pk_mul_f32 v[46:47], v[46:47], v[146:147]
	v_pk_mul_f32 v[42:43], v[42:43], v[150:151]
	v_pk_mul_f32 v[38:39], v[38:39], v[154:155]
	v_pk_mul_f32 v[34:35], v[34:35], v[158:159]
	v_pk_mul_f32 v[32:33], v[32:33], v[148:149]
	v_pk_mul_f32 v[28:29], v[28:29], v[152:153]
	v_pk_mul_f32 v[24:25], v[24:25], v[156:157]
	v_pk_mul_f32 v[20:21], v[20:21], v[160:161]
	v_pk_mul_f32 v[30:31], v[30:31], v[146:147]
	v_pk_mul_f32 v[26:27], v[26:27], v[150:151]
	v_pk_mul_f32 v[22:23], v[22:23], v[154:155]
	v_pk_mul_f32 v[18:19], v[18:19], v[158:159]

; #define SBAR() __builtin_amdgcn_sched_barrier(0)
; #define BIASADD(P0, P1, kt0) do { if constexpr (BIAS) { const int dlo_ = (kt0) - q0 - 255, dhi_ = (kt0) + 63 - q0; \
;     if (!(dlo_ >= 1024) && !(dhi_ <= -1024)) { const float* tb_ = tbl_l + ((kt0) - qlane + TOFF + 4 * hi); \
;       _Pragma("unroll") for (int r = 0; r < 16; ++r) { P0[r] += tb_[(r & 3) + 8 * (r >> 2)]; P1[r] += tb_[32 + (r & 3) + 8 * (r >> 2)]; } } } } while (0)
; #define NEGM_UPD(kt0) do { float nmj_ = -mC; if constexpr (BIAS) { const int dlo_ = (kt0) - q0 - 255, dhi_ = (kt0) + 63 - q0; if (dlo_ >= 1024) nmj_ += cb_hi; else if (dhi_ <= -1024) nmj_ += cb_lo; } \
;     if (__any(nmj_ != nm_cur)) { nm_cur = nmj_; _Pragma("unroll") for (int r = 0; r < 16; ++r) negm[r] = nmj_; } } while (0)
; #define QKT(P0, P1, KOFF) do { if constexpr (NDQ == 8 && NQL == 0) qkt8_roll(P0, P1, negm, kb0 + (KOFF), qr); \
;     else if constexpr (NDQ == 12 && NQL == 4) qkt12_roll(P0, P1, negm, kb0 + (KOFF), qa0, qr); else qkt<NDQ, NQL>(P0, P1, negm, K_lds + (KOFF), qr, qls, r32, hi); } while (0)
; template <bool EXP1 = true>
; __device__ __forceinline__ void finishSM(f32x16& p0, f32x16& p1, float alpha, float& l_reg, bf16x8& pa0, bf16x8& pa1, bf16x8& pa2, bf16x8& pa3) {
;   if constexpr (EXP1) {
; #pragma unroll
;   for (int r = 0; r < 16; ++r) p1[r] = __builtin_amdgcn_exp2f(p1[r]);
;   }
;   float sm_[4] = {p0[0], p0[1], p0[2], p0[3]};
; #pragma unroll
;   for (int r = 4; r < 16; ++r) sm_[r & 3] += p0[r];
; #pragma unroll
;   for (int r = 0; r < 16; ++r) sm_[r & 3] += p1[r];
;   float ps = (sm_[0] + sm_[1]) + (sm_[2] + sm_[3]);
;   { auto rr = __builtin_amdgcn_permlane32_swap(__float_as_uint(ps), __float_as_uint(ps), false, false);
;     ps = __uint_as_float(rr[0]) + __uint_as_float(rr[1]); }
;   l_reg = l_reg * alpha + ps;
;     ...
;   PK4(p0, 0, pa0); PK4(p0, 8, pa1); PK4(p1, 0, pa2); PK4(p1, 8, pa3);
;     ...
; }
;     ...
;   NEGM_UPD(kbeg + (NT - 1) * KVBLK); SBAR(); QKT(pB0, pB1, SHM_K);
;   finishSM<!SLICED>(pA0, pA1, alA, l_reg, pa0, pa1, pa2, pa3); SBAR();
;   pv_d0(o, vb0, pa0, pa1, pa2, pa3); BIASADD(pB0, pB1, kbeg + (NT - 1) * KVBLK); partialSM<false>(pB0, pB1, mC, alB);
.LBB0_437:
	v_lshl_add_u64 v[252:253], v[186:187], 0, v[0:1]
	v_add_co_u32_e64 v252, s[6:7], s78, v252
	s_nop 1
	v_addc_co_u32_e64 v253, s[6:7], 0, v253, s[6:7]
	v_cmp_neq_f32_e64 s[6:7], v232, -v227
	s_cmp_eq_u64 s[6:7], 0
	s_cselect_b64 s[6:7], -1, 0
	v_cndmask_b32_e64 v97, -v227, v97, s[6:7]
	v_cndmask_b32_e64 v96, -v227, v96, s[6:7]
	v_cndmask_b32_e64 v95, -v227, v95, s[6:7]
	v_cndmask_b32_e64 v94, -v227, v94, s[6:7]
	v_cndmask_b32_e64 v93, -v227, v93, s[6:7]
	v_cndmask_b32_e64 v92, -v227, v92, s[6:7]
	v_cndmask_b32_e64 v91, -v227, v91, s[6:7]
	v_cndmask_b32_e64 v90, -v227, v90, s[6:7]
	v_cndmask_b32_e64 v89, -v227, v89, s[6:7]
	v_cndmask_b32_e64 v88, -v227, v88, s[6:7]
	v_cndmask_b32_e64 v87, -v227, v87, s[6:7]
	v_cndmask_b32_e64 v86, -v227, v86, s[6:7]
	v_cndmask_b32_e64 v85, -v227, v85, s[6:7]
	v_cndmask_b32_e64 v84, -v227, v84, s[6:7]
	v_cndmask_b32_e64 v83, -v227, v83, s[6:7]
	v_cndmask_b32_e64 v82, -v227, v82, s[6:7]
	ds_read_b128 v[162:165], v224 offset:0
	ds_read_b128 v[166:169], v224 offset:0x2000
	ds_read_b128 v[170:173], v223 offset:0
	ds_read_b128 v[174:177], v223 offset:0x2000
	ds_read_b128 v[184:187], v222 offset:0
	ds_read_b128 v[188:191], v222 offset:0x2000
	s_waitcnt lgkmcnt(4)
	s_nop 1
	v_mfma_f32_32x32x16_bf16 v[98:113], v[162:165], v[142:145], v[82:97]
	v_mfma_f32_32x32x16_bf16 v[82:97], v[166:169], v[142:145], v[82:97]
	ds_read_b128 v[142:145], v221 offset:0
	ds_read_b128 v[162:165], v221 offset:0x2000
	s_waitcnt lgkmcnt(4)
	v_mfma_f32_32x32x16_bf16 v[98:113], v[170:173], v[138:141], v[98:113]
	v_mfma_f32_32x32x16_bf16 v[82:97], v[174:177], v[138:141], v[82:97]
	ds_read_b128 v[138:141], v220 offset:0
	ds_read_b128 v[166:169], v220 offset:0x2000
	s_waitcnt lgkmcnt(4)
	v_mfma_f32_32x32x16_bf16 v[98:113], v[184:187], v[134:137], v[98:113]
	v_mfma_f32_32x32x16_bf16 v[82:97], v[188:191], v[134:137], v[82:97]
	ds_read_b128 v[134:137], v219 offset:0
	ds_read_b128 v[170:173], v219 offset:0x2000
	s_waitcnt lgkmcnt(4)
	v_mfma_f32_32x32x16_bf16 v[98:113], v[142:145], v[130:133], v[98:113]
	v_mfma_f32_32x32x16_bf16 v[82:97], v[162:165], v[130:133], v[82:97]
	ds_read_b128 v[130:133], v218 offset:0
	ds_read_b128 v[142:145], v218 offset:0x2000
	s_waitcnt lgkmcnt(4)
	v_mfma_f32_32x32x16_bf16 v[98:113], v[138:141], v[126:129], v[98:113]
	v_mfma_f32_32x32x16_bf16 v[82:97], v[166:169], v[126:129], v[82:97]
	ds_read_b128 v[126:129], v217 offset:0
	ds_read_b128 v[138:141], v217 offset:0x2000
	s_waitcnt lgkmcnt(4)
	v_mfma_f32_32x32x16_bf16 v[98:113], v[134:137], v[122:125], v[98:113]
	s_waitcnt lgkmcnt(2)
	v_mfma_f32_32x32x16_bf16 v[82:97], v[170:173], v[122:125], v[82:97]
	v_mfma_f32_32x32x16_bf16 v[98:113], v[130:133], v[118:121], v[98:113]
	s_waitcnt lgkmcnt(0)
	v_mfma_f32_32x32x16_bf16 v[82:97], v[142:145], v[118:121], v[82:97]
	v_mfma_f32_32x32x16_bf16 v[98:113], v[126:129], v[114:117], v[98:113]
	v_exp_f32_e32 v118, v69
	v_exp_f32_e32 v119, v70
	v_exp_f32_e32 v120, v71
	v_exp_f32_e32 v121, v72
	v_exp_f32_e32 v122, v73
	v_add_f32_e32 v0, v148, v146
	v_exp_f32_e32 v123, v74
	v_mfma_f32_32x32x16_bf16 v[82:97], v[138:141], v[114:117], v[82:97]
	v_exp_f32_e32 v115, v66
	v_exp_f32_e32 v116, v67
	v_exp_f32_e32 v117, v68
	v_add_f32_e32 v66, v159, v161
	v_add_f32_e32 v67, v149, v147
	v_add_f32_e32 v68, v158, v160
	v_exp_f32_e32 v124, v75
	v_exp_f32_e32 v125, v76
	v_exp_f32_e32 v126, v77
	v_add_f32_e32 v0, v150, v0
	v_add_f32_e32 v66, v157, v66
	v_add_f32_e32 v67, v151, v67
	v_add_f32_e32 v68, v156, v68
	v_exp_f32_e32 v127, v78
	v_exp_f32_e32 v128, v79
	v_exp_f32_e32 v129, v80
	v_exp_f32_e32 v81, v81
	v_add_f32_e32 v0, v152, v0
	v_add_f32_e32 v66, v155, v66
	v_add_f32_e32 v67, v153, v67
	v_add_f32_e32 v68, v154, v68
	v_add_f32_e32 v0, v0, v115
	v_add_f32_e32 v66, v66, v116
	v_add_f32_e32 v67, v67, v117
	v_add_f32_e32 v68, v68, v118
	v_add_f32_e32 v0, v119, v0
	v_add_f32_e32 v66, v120, v66
	v_add_f32_e32 v67, v121, v67
	v_add_f32_e32 v68, v122, v68
	v_add_f32_e32 v0, v123, v0
	v_add_f32_e32 v66, v124, v66
	v_add_f32_e32 v67, v125, v67
	v_add_f32_e32 v68, v126, v68
	v_add_f32_e32 v0, v127, v0
	v_add_f32_e32 v66, v128, v66
	v_add_f32_e32 v67, v129, v67
	v_add_f32_e32 v68, v81, v68
	v_add_f32_e32 v0, v0, v66
	v_add_f32_e32 v66, v67, v68
	v_add_f32_e32 v0, v0, v66
	v_mov_b32_e32 v114, v0
	v_cvt_pk_bf16_f32 v66, v146, v161
	v_cvt_pk_bf16_f32 v67, v147, v160
	v_cvt_pk_bf16_f32 v68, v148, v159
	s_nop 1
	v_permlane32_swap_b32_e32 v0, v114
	v_cvt_pk_bf16_f32 v69, v149, v158
	v_permlane32_swap_b32_e32 v66, v68
	v_cvt_pk_bf16_f32 v70, v150, v157
	v_cvt_pk_bf16_f32 v71, v151, v156
	v_cvt_pk_bf16_f32 v72, v152, v155
	v_cvt_pk_bf16_f32 v73, v153, v154
	v_cvt_pk_bf16_f32 v74, v115, v116
	v_cvt_pk_bf16_f32 v75, v117, v118
	v_cvt_pk_bf16_f32 v76, v119, v120
	v_cvt_pk_bf16_f32 v77, v121, v122
	v_cvt_pk_bf16_f32 v78, v123, v124
	v_cvt_pk_bf16_f32 v79, v125, v126
	v_cvt_pk_bf16_f32 v80, v127, v128
	v_cvt_pk_bf16_f32 v81, v129, v81
	v_permlane32_swap_b32_e32 v67, v69
	v_permlane32_swap_b32_e32 v70, v72
	v_permlane32_swap_b32_e32 v71, v73
	v_permlane32_swap_b32_e32 v74, v76
	v_permlane32_swap_b32_e32 v75, v77
	v_permlane32_swap_b32_e32 v78, v80
	v_permlane32_swap_b32_e32 v79, v81
	ds_read_b64_tr_b16 v[116:117], v199 offset:0
	ds_read_b64_tr_b16 v[118:119], v199 offset:0x800
	ds_read_b64_tr_b16 v[120:121], v199 offset:0x1000
	ds_read_b64_tr_b16 v[122:123], v199 offset:0x1800
	ds_read_b64_tr_b16 v[124:125], v199 offset:0x2000
	ds_read_b64_tr_b16 v[126:127], v199 offset:0x2800
	ds_read_b64_tr_b16 v[128:129], v199 offset:0x3000
	ds_read_b64_tr_b16 v[130:131], v199 offset:0x3800
	ds_read_b64_tr_b16 v[132:133], v199 offset:0x200
	ds_read_b64_tr_b16 v[134:135], v199 offset:0xa00
	s_waitcnt lgkmcnt(8)
; __device__ __forceinline__ void pv_d0(f32x16* o, int vb, bf16x8 pa0, bf16x8 pa1, bf16x8 pa2, bf16x8 pa3) {
;     ...
;   const s16x4 l0 = tr_read<v_rd_off(0, 0, 0)>(vb), h0 = tr_read<v_rd_off(0, 0, 1)>(vb);
;   const s16x4 l1 = tr_read<v_rd_off(0, 1, 0)>(vb), h1 = tr_read<v_rd_off(0, 1, 1)>(vb);
;   const s16x4 l2 = tr_read<v_rd_off(0, 2, 0)>(vb), h2 = tr_read<v_rd_off(0, 2, 1)>(vb);
;   const s16x4 l3 = tr_read<v_rd_off(0, 3, 0)>(vb), h3 = tr_read<v_rd_off(0, 3, 1)>(vb);
;   const s16x4 l4 = tr_read<v_rd_off(1, 0, 0)>(vb), h4 = tr_read<v_rd_off(1, 0, 1)>(vb);
;   asm volatile("s_waitcnt lgkmcnt(8)" ::: "memory"); SBAR();
;   o[0] = __builtin_amdgcn_mfma_f32_32x32x16_bf16(pa0, PK(l0, h0), o[0], 0, 0, 0);
;   const s16x4 l5 = tr_read<v_rd_off(1, 1, 0)>(vb), h5 = tr_read<v_rd_off(1, 1, 1)>(vb);
;   asm volatile("s_waitcnt lgkmcnt(8)" ::: "memory"); SBAR();
;   o[0] = __builtin_amdgcn_mfma_f32_32x32x16_bf16(pa1, PK(l1, h1), o[0], 0, 0, 0);
;   const s16x4 l6 = tr_read<v_rd_off(1, 2, 0)>(vb), h6 = tr_read<v_rd_off(1, 2, 1)>(vb);
;   asm volatile("s_waitcnt lgkmcnt(8)" ::: "memory"); SBAR();
;   o[0] = __builtin_amdgcn_mfma_f32_32x32x16_bf16(pa2, PK(l2, h2), o[0], 0, 0, 0);
;   const s16x4 l7 = tr_read<v_rd_off(1, 3, 0)>(vb), h7 = tr_read<v_rd_off(1, 3, 1)>(vb);
;   asm volatile("s_waitcnt lgkmcnt(8)" ::: "memory"); SBAR();
;   o[0] = __builtin_amdgcn_mfma_f32_32x32x16_bf16(pa3, PK(l3, h3), o[0], 0, 0, 0);
;   const s16x4 l8 = tr_read<v_rd_off(2, 0, 0)>(vb), h8 = tr_read<v_rd_off(2, 0, 1)>(vb);
;   asm volatile("s_waitcnt lgkmcnt(8)" ::: "memory"); SBAR();
;   o[1] = __builtin_amdgcn_mfma_f32_32x32x16_bf16(pa0, PK(l4, h4), o[1], 0, 0, 0);
;   const s16x4 l9 = tr_read<v_rd_off(2, 1, 0)>(vb), h9 = tr_read<v_rd_off(2, 1, 1)>(vb);
;   asm volatile("s_waitcnt lgkmcnt(8)" ::: "memory"); SBAR();
;   o[1] = __builtin_amdgcn_mfma_f32_32x32x16_bf16(pa1, PK(l5, h5), o[1], 0, 0, 0);
;   const s16x4 l10 = tr_read<v_rd_off(2, 2, 0)>(vb), h10 = tr_read<v_rd_off(2, 2, 1)>(vb);
;   asm volatile("s_waitcnt lgkmcnt(8)" ::: "memory"); SBAR();
;   o[1] = __builtin_amdgcn_mfma_f32_32x32x16_bf16(pa2, PK(l6, h6), o[1], 0, 0, 0);
;   const s16x4 l11 = tr_read<v_rd_off(2, 3, 0)>(vb), h11 = tr_read<v_rd_off(2, 3, 1)>(vb);
;     ...
;   pv_d0(o, vb0, pa0, pa1, pa2, pa3); BIASADD(pB0, pB1, kbeg + (NT - 1) * KVBLK); partialSM<false>(pB0, pB1, mC, alB);
;   __syncthreads(); RESC(alB);
	s_nop 0
	v_mfma_f32_32x32x16_bf16 v[2:17], v[66:69], v[116:119], v[2:17]
	ds_read_b64_tr_b16 v[116:117], v199 offset:0x1200
	ds_read_b64_tr_b16 v[118:119], v199 offset:0x1a00
	s_waitcnt lgkmcnt(8)
	v_mfma_f32_32x32x16_bf16 v[2:17], v[70:73], v[120:123], v[2:17]
	ds_read_b64_tr_b16 v[120:121], v199 offset:0x2200
	ds_read_b64_tr_b16 v[122:123], v199 offset:0x2a00
	s_waitcnt lgkmcnt(8)
	v_mfma_f32_32x32x16_bf16 v[2:17], v[74:77], v[124:127], v[2:17]
	ds_read_b64_tr_b16 v[124:125], v199 offset:0x3200
	ds_read_b64_tr_b16 v[126:127], v199 offset:0x3a00
	s_waitcnt lgkmcnt(8)
	v_mfma_f32_32x32x16_bf16 v[2:17], v[78:81], v[128:131], v[2:17]
	ds_read_b64_tr_b16 v[128:129], v199 offset:0x400
	ds_read_b64_tr_b16 v[130:131], v199 offset:0xc00
	s_waitcnt lgkmcnt(8)
	v_mfma_f32_32x32x16_bf16 v[50:65], v[66:69], v[132:135], v[50:65]
	ds_read_b64_tr_b16 v[132:133], v199 offset:0x1400
	ds_read_b64_tr_b16 v[134:135], v199 offset:0x1c00
	s_waitcnt lgkmcnt(8)
	v_mfma_f32_32x32x16_bf16 v[50:65], v[70:73], v[116:119], v[50:65]
	ds_read_b64_tr_b16 v[116:117], v199 offset:0x2400
	ds_read_b64_tr_b16 v[118:119], v199 offset:0x2c00
	s_waitcnt lgkmcnt(8)
	v_mfma_f32_32x32x16_bf16 v[50:65], v[74:77], v[120:123], v[50:65]
	ds_read_b64_tr_b16 v[120:121], v199 offset:0x3400
	ds_read_b64_tr_b16 v[122:123], v199 offset:0x3c00
	s_waitcnt lgkmcnt(8)
	v_mfma_f32_32x32x16_bf16 v[50:65], v[78:81], v[124:127], v[50:65]
	ds_read_b64_tr_b16 v[124:125], v199 offset:0x600
	ds_read_b64_tr_b16 v[126:127], v199 offset:0xe00
	s_waitcnt lgkmcnt(8)
	v_mfma_f32_32x32x16_bf16 v[34:49], v[66:69], v[128:131], v[34:49]
	ds_read_b64_tr_b16 v[128:129], v199 offset:0x1600
	ds_read_b64_tr_b16 v[130:131], v199 offset:0x1e00
	s_waitcnt lgkmcnt(8)
	v_mfma_f32_32x32x16_bf16 v[34:49], v[70:73], v[132:135], v[34:49]
	ds_read_b64_tr_b16 v[132:133], v199 offset:0x2600
	ds_read_b64_tr_b16 v[134:135], v199 offset:0x2e00
	s_waitcnt lgkmcnt(8)
	v_mfma_f32_32x32x16_bf16 v[34:49], v[74:77], v[116:119], v[34:49]
	ds_read_b64_tr_b16 v[116:117], v199 offset:0x3600
	ds_read_b64_tr_b16 v[118:119], v199 offset:0x3e00
	s_waitcnt lgkmcnt(8)
	v_mfma_f32_32x32x16_bf16 v[34:49], v[78:81], v[120:123], v[34:49]
	s_waitcnt lgkmcnt(6)
	v_mfma_f32_32x32x16_bf16 v[18:33], v[66:69], v[124:127], v[18:33]
	s_waitcnt lgkmcnt(4)
	v_mfma_f32_32x32x16_bf16 v[18:33], v[70:73], v[128:131], v[18:33]
	s_waitcnt lgkmcnt(2)
	v_mfma_f32_32x32x16_bf16 v[18:33], v[74:77], v[132:135], v[18:33]
	s_waitcnt lgkmcnt(0)
	v_max_f32_e32 v66, v102, v102
	v_max_f32_e32 v67, v98, v98
	v_max_f32_e32 v66, v67, v66
	v_max_f32_e32 v67, v103, v103
	v_max_f32_e32 v68, v99, v99
	v_max_f32_e32 v67, v68, v67
	v_max_f32_e32 v68, v105, v105
	v_max_f32_e32 v69, v101, v101
	v_max_f32_e32 v68, v69, v68
	v_max3_f32 v69, v100, v104, v108
	v_max3_f32 v68, v68, v109, v113
	v_max3_f32 v66, v66, v106, v110
	v_max3_f32 v67, v67, v107, v111
	v_max3_f32 v69, v69, v112, v84
	v_max3_f32 v68, v68, v85, v89
	v_max3_f32 v66, v66, v82, v86
	v_max3_f32 v67, v67, v83, v87
	v_max3_f32 v69, v69, v88, v92
	v_max3_f32 v68, v68, v93, v97
	v_mfma_f32_32x32x16_bf16 v[18:33], v[78:81], v[116:119], v[18:33]
	v_max3_f32 v66, v66, v90, v94
	v_max3_f32 v67, v67, v91, v95
	v_max3_f32 v68, v69, v96, v68
	v_max3_f32 v66, v66, v67, v68
	v_mov_b32_e32 v67, v66
	s_nop 1
	v_permlane32_swap_b32_e32 v66, v67
	v_max_f32_e32 v67, v67, v67
	v_max_f32_e32 v66, v66, v66
	v_max_f32_e32 v66, v66, v67
	v_cmp_ge_f32_e32 vcc, s48, v66
	s_cmp_lg_u64 vcc, exec
	v_mov_b32_e32 v115, 1.0
	s_cbranch_scc1 .LBB0_470
.LBB0_438:
	global_load_dwordx4 v[202:205], v[252:253], off offset:2176
	v_add_co_u32_e32 v252, vcc, 0x50000, v252
	s_nop 1
	v_addc_co_u32_e32 v253, vcc, 0, v253, vcc
	s_waitcnt vmcnt(0)
	ds_write_b128 v201, v[202:205] offset:16384
	s_waitcnt lgkmcnt(0)
	global_load_dwordx4 v[202:205], v[252:253], off offset:2176
	s_waitcnt vmcnt(0)
	ds_write_b128 v207, v[202:205] offset:16384
	s_waitcnt lgkmcnt(0)
	v_cmp_gt_f32_e32 vcc, 1.0, v115
	s_barrier
	s_cbranch_vccz .LBB0_442
	s_and_saveexec_b64 s[6:7], s[4:5]
	ds_write_b32 v183, v115 offset:128
	s_or_b64 exec, exec, s[6:7]
	s_waitcnt lgkmcnt(0)
	ds_read_b128 v[66:69], v181 offset:224
	ds_read_b128 v[70:73], v181 offset:192
	ds_read_b128 v[74:77], v181 offset:160
	ds_read_b128 v[78:81], v181 offset:128
	s_waitcnt lgkmcnt(3)
	v_pk_mul_f32 v[16:17], v[16:17], v[68:69]
	s_waitcnt lgkmcnt(2)
	v_pk_mul_f32 v[12:13], v[12:13], v[72:73]
	s_waitcnt lgkmcnt(1)
	v_pk_mul_f32 v[8:9], v[8:9], v[76:77]
	s_waitcnt lgkmcnt(0)
	v_pk_mul_f32 v[4:5], v[4:5], v[80:81]
	v_pk_mul_f32 v[14:15], v[14:15], v[66:67]
	v_pk_mul_f32 v[10:11], v[10:11], v[70:71]
	v_pk_mul_f32 v[6:7], v[6:7], v[74:75]
	v_pk_mul_f32 v[2:3], v[2:3], v[78:79]
	v_pk_mul_f32 v[64:65], v[64:65], v[68:69]
	v_pk_mul_f32 v[60:61], v[60:61], v[72:73]
	v_pk_mul_f32 v[56:57], v[56:57], v[76:77]
	v_pk_mul_f32 v[52:53], v[52:53], v[80:81]
	v_pk_mul_f32 v[62:63], v[62:63], v[66:67]
	v_pk_mul_f32 v[58:59], v[58:59], v[70:71]
	v_pk_mul_f32 v[54:55], v[54:55], v[74:75]
	v_pk_mul_f32 v[50:51], v[50:51], v[78:79]
	v_pk_mul_f32 v[48:49], v[48:49], v[68:69]
	v_pk_mul_f32 v[44:45], v[44:45], v[72:73]
	v_pk_mul_f32 v[40:41], v[40:41], v[76:77]
	v_pk_mul_f32 v[36:37], v[36:37], v[80:81]
	v_pk_mul_f32 v[46:47], v[46:47], v[66:67]
	v_pk_mul_f32 v[42:43], v[42:43], v[70:71]
	v_pk_mul_f32 v[38:39], v[38:39], v[74:75]
	v_pk_mul_f32 v[34:35], v[34:35], v[78:79]
	v_pk_mul_f32 v[32:33], v[32:33], v[68:69]
	v_pk_mul_f32 v[28:29], v[28:29], v[72:73]
	v_pk_mul_f32 v[24:25], v[24:25], v[76:77]
	v_pk_mul_f32 v[20:21], v[20:21], v[80:81]
	v_pk_mul_f32 v[30:31], v[30:31], v[66:67]
	v_pk_mul_f32 v[26:27], v[26:27], v[70:71]
	v_pk_mul_f32 v[22:23], v[22:23], v[74:75]
	v_pk_mul_f32 v[18:19], v[18:19], v[78:79]

;     ...
;   int tid_ = wave0 * 64 + lane_id_v();
;   const int tid = tid_, wid = tid >> 6, lane = tid & 63, r32 = lane & 31, hi = lane >> 5;
;   char* V_lds = lds; char* K_lds = lds + LDS_K_OFF;
;   float* ws = (float*)(lds + LDS_WS_OFF) + wid * 64; float* li_l = ws; float* al_l = ws + 32;
;   float* tbl_l = (float*)(lds + LDS_TBL_OFF);
;   __syncthreads();
;   if constexpr (BIAS) { for (int i = tid; i < TBLN; i += 512) tbl_l[i] = tblg[i]; }
;   float mC = 0.f, l_reg = 0, nm_cur = 0.f; f32x16 o[4] = {}; f32x16 negm = {}; bf16x8 qr[NDQ - NQL];
;   const bf16_t* Qw = Qb + (long)(wid * QBLK + r32) * ldq + hi * 8;
;   char* qls = lds + LDS_Q_OFF + wid * 8192 + lane * 16;
; #pragma unroll
;   for (int d0 = 0; d0 < NDQ - NQL; ++d0) qr[d0] = *reinterpret_cast<const bf16x8*>(Qw + d0 * 16);
;   if constexpr (ROPEQ) {
;     static_assert(NDQ == 12 && NQL >= 4, "ROPEQ: MLA layout");
; #pragma unroll
;     for (int d0 = NDQ - NQL; d0 < 8; ++d0) *reinterpret_cast<bf16x8*>(qls + (d0 - (NDQ - NQL)) * 1024) = *reinterpret_cast<const bf16x8*>(Qw + d0 * 16);
;     const int qrow = q0 + wid * QBLK + r32;
; #pragma unroll
;     for (int pr = 0; pr < 2; ++pr) {
;       const bf16x8 xa = *reinterpret_cast<const bf16x8*>(Qw + (8 + pr) * 16), xb = *reinterpret_cast<const bf16x8*>(Qw + (10 + pr) * 16);
;       const float* cp = cosp + (size_t)qrow * 32 + pr * 16 + hi * 8; const float* sp = sinp + (size_t)qrow * 32 + pr * 16 + hi * 8;
;       const f32x4 c0 = *(const f32x4*)cp, c1 = *(const f32x4*)(cp + 4), s0 = *(const f32x4*)sp, s1 = *(const f32x4*)(sp + 4);
;       float ya[8], yb[8];
; #pragma unroll
;       for (int t = 0; t < 8; ++t) { const float x1 = bf2f((unsigned short)xa[t]), x2 = bf2f((unsigned short)xb[t]); const float c = t < 4 ? c0[t & 3] : c1[t & 3], sn = t < 4 ? s0[t & 3] : s1[t & 3];
;         ya[t] = x1 * c - x2 * sn; yb[t] = x2 * c + x1 * sn; }
;       u32x4 wa = {pk2(ya[0], ya[1]), pk2(ya[2], ya[3]), pk2(ya[4], ya[5]), pk2(ya[6], ya[7])}, wb = {pk2(yb[0], yb[1]), pk2(yb[2], yb[3]), pk2(yb[4], yb[5]), pk2(yb[6], yb[7])};
;       *reinterpret_cast<u32x4*>(qls + (8 + pr - (NDQ - NQL)) * 1024) = wa; *reinterpret_cast<u32x4*>(qls + (10 + pr - (NDQ - NQL)) * 1024) = wb; }
;   } else {
; #pragma unroll
;   for (int d0 = NDQ - NQL; d0 < NDQ; ++d0) *reinterpret_cast<bf16x8*>(qls + (d0 - (NDQ - NQL)) * 1024) = *reinterpret_cast<const bf16x8*>(Qw + d0 * 16);
;   }
.LBB0_445:
	s_and_b64 vcc, exec, s[4:5]
	s_cbranch_vccz .LBB0_418
	v_readlane_b32 s4, v254, 21
	v_mbcnt_lo_u32_b32 v22, -1, 0
	v_mbcnt_hi_u32_b32 v22, -1, v22
	v_mov_b64_e32 v[54:55], s[58:59]
	v_lshlrev_b32_e32 v24, 3, v22
	v_add_u32_e32 v23, s4, v22
	v_ashrrev_i32_e32 v50, 4, v23
	v_and_b32_e32 v0, 0x78, v24
	v_lshlrev_b32_e32 v0, 1, v0
	v_mad_i64_i32 v[2:3], s[4:5], v50, s55, v[54:55]
	v_lshl_add_u64 v[2:3], v[2:3], 0, v[0:1]
	s_waitcnt lgkmcnt(0)
	s_barrier
	v_add_u32_e32 v18, 32, v50
	global_load_dwordx4 v[2:5], v[2:3], off
	v_ashrrev_i32_e32 v51, 31, v50
	v_mad_i64_i32 v[6:7], s[4:5], v18, s55, v[54:55]
	v_ashrrev_i32_e32 v19, 31, v18
	v_lshlrev_b64 v[52:53], 9, v[50:51]
	v_lshlrev_b64 v[14:15], 9, v[18:19]
	v_ashrrev_i32_e32 v19, 1, v23
	s_movk_i32 s4, 0xffe0
	v_lshl_add_u64 v[10:11], s[50:51], 0, v[52:53]
	v_lshl_add_u64 v[14:15], s[50:51], 0, v[14:15]
	v_bfi_b32 v20, s4, v19, v22
	v_lshl_add_u64 v[6:7], v[6:7], 0, v[0:1]
	v_lshl_add_u64 v[10:11], v[10:11], 0, v[0:1]
	v_lshl_add_u64 v[14:15], v[14:15], 0, v[0:1]
	v_ashrrev_i32_e32 v21, 31, v20
	v_bfe_u32 v196, v22, 5, 1
	global_load_dwordx4 v[6:9], v[6:7], off
	v_lshlrev_b64 v[20:21], 10, v[20:21]
	global_load_dwordx4 v[10:13], v[10:11], off
	v_lshl_add_u64 v[20:21], s[56:57], 0, v[20:21]
	global_load_dwordx4 v[14:17], v[14:15], off
	v_lshlrev_b32_e32 v182, 4, v196
	v_mov_b32_e32 v183, v1
	v_lshl_add_u64 v[20:21], v[20:21], 0, v[182:183]
	global_load_dwordx4 v[158:161], v[20:21], off
	global_load_dwordx4 v[154:157], v[20:21], off offset:32
	global_load_dwordx4 v[150:153], v[20:21], off offset:64
	global_load_dwordx4 v[146:149], v[20:21], off offset:96
	global_load_dwordx4 v[142:145], v[20:21], off offset:128
	global_load_dwordx4 v[138:141], v[20:21], off offset:160
	global_load_dwordx4 v[134:137], v[20:21], off offset:192
	global_load_dwordx4 v[130:133], v[20:21], off offset:224
	v_and_b32_e32 v20, 0x3fffffc0, v23
	s_add_i32 s4, 0, 0x14000
	v_lshl_add_u32 v179, v20, 2, s4
	v_and_b32_e32 v180, 0xffffffe0, v19
	v_and_b32_e32 v19, 0xfffff0, v50
	v_lshlrev_b32_e32 v20, 1, v50
	v_and_or_b32 v19, v20, 8, v19
	v_lshrrev_b32_e32 v20, 1, v50
	v_lshrrev_b32_e32 v19, 1, v19
	v_bfe_u32 v21, v24, 5, 2
	v_and_b32_e32 v24, 3, v50
	v_or_b32_e32 v19, v19, v21
	v_and_or_b32 v20, v20, 4, v24
	v_and_b32_e32 v25, 0xfffff0, v18
	v_lshlrev_b32_e32 v26, 1, v18
	v_lshlrev_b32_e32 v19, 9, v19
	v_lshlrev_b32_e32 v20, 6, v20
	v_and_b32_e32 v24, 48, v0
	v_and_or_b32 v25, v26, 8, v25
	v_or3_b32 v19, v19, v20, v24
	v_lshrrev_b32_e32 v25, 1, v25
	v_or_b32_e32 v21, v25, v21
	v_add_u32_e32 v201, 0, v19
	v_lshlrev_b32_e32 v21, 9, v21
	s_waitcnt vmcnt(0)
	v_and_b32_e32 v51, 63, v22
	v_or3_b32 v20, v21, v20, v24
	v_lshlrev_b32_e32 v24, 4, v22
	s_cmp_lg_u32 0, -1
	v_lshlrev_b32_e32 v21, 3, v51
	v_and_b32_e32 v24, 0xc0, v24
	v_lshlrev_b32_e32 v25, 1, v22
	s_cselect_b32 s6, 0, 0
	s_add_i32 s4, 0, 0x8000
	v_and_b32_e32 v178, 31, v22
	v_and_or_b32 v24, v21, 24, v24
	v_and_b32_e32 v25, 32, v25
	v_and_b32_e32 v21, 0x100, v21
	s_cmp_lg_u32 s4, -1
	v_and_b32_e32 v87, 15, v22
	v_bitop3_b32 v22, v196, v22, 15 bitop3:0x78
	v_or3_b32 v86, v24, v25, v21
	v_lshlrev_b32_e32 v21, 8, v178
	s_cselect_b32 s4, s4, 0
	v_lshlrev_b32_e32 v22, 4, v22
	v_add_u32_e32 v207, 0, v20
	v_add3_u32 v200, v21, s4, v22
	v_xor_b32_e32 v210, 32, v200
	v_xor_b32_e32 v211, 64, v200
	s_mov_b32 s56, -1
	v_add_u32_e32 v199, s6, v86
	s_waitcnt vmcnt(11)
	ds_write_b128 v201, v[2:5]
	v_lshlrev_b32_e32 v2, 8, v50
	v_and_b32_e32 v3, 0xf0, v23
	v_bitop3_b32 v2, v0, v2, v3 bitop3:0xde
	v_add_u32_e32 v208, 0, v2
	v_lshlrev_b32_e32 v2, 8, v18
	v_bitop3_b32 v2, v2, v0, v3 bitop3:0xf6
	v_add_u32_e32 v209, 0, v2
	s_waitcnt vmcnt(10)
	ds_write_b128 v207, v[6:9]
	s_waitcnt vmcnt(9)
	ds_write_b128 v208, v[10:13] offset:32768
	s_waitcnt vmcnt(8)
	ds_write_b128 v209, v[14:17] offset:32768
	s_waitcnt lgkmcnt(0)
	s_barrier
	ds_read_b128 v[2:5], v200 offset:0
	ds_read_b128 v[18:21], v200 offset:0x2000
	ds_read_b128 v[56:59], v210 offset:0
	ds_read_b128 v[60:63], v210 offset:0x2000
	ds_read_b128 v[64:67], v211 offset:0
	ds_read_b128 v[68:71], v211 offset:0x2000
	s_waitcnt lgkmcnt(4)
	s_waitcnt vmcnt(7)
	v_mfma_f32_32x32x16_bf16 v[34:49], v[2:5], v[158:161], 0
	v_xor_b32_e32 v212, 0x60, v200
	ds_read_b128 v[72:75], v212 offset:0
	ds_read_b128 v[76:79], v212 offset:0x2000
	s_mov_b32 s13, s12
	s_waitcnt lgkmcnt(4)
	s_mov_b32 s14, s12
	s_mov_b32 s15, s12
	v_mfma_f32_32x32x16_bf16 v[18:33], v[18:21], v[158:161], 0
	s_mov_b32 s16, s12
	s_mov_b32 s17, s12
	s_mov_b32 s18, s12
	s_mov_b32 s19, s12
	s_mov_b32 s20, s12
	s_mov_b32 s21, s12
	s_mov_b32 s22, s12
	s_mov_b32 s23, s12
	s_mov_b32 s24, s12
	s_mov_b32 s25, s12
	s_mov_b32 s26, s12
	s_mov_b32 s27, s12
	v_mov_b64_e32 v[2:3], s[12:13]
	v_mov_b64_e32 v[4:5], s[14:15]
	v_mov_b64_e32 v[6:7], s[16:17]
	v_mov_b64_e32 v[8:9], s[18:19]
	v_mov_b64_e32 v[10:11], s[20:21]
	v_mov_b64_e32 v[12:13], s[22:23]
	v_mov_b64_e32 v[14:15], s[24:25]
	v_mov_b64_e32 v[16:17], s[26:27]
	s_waitcnt vmcnt(6)
	v_mfma_f32_32x32x16_bf16 v[34:49], v[56:59], v[154:157], v[34:49]
	v_xor_b32_e32 v213, 0x80, v200
	ds_read_b128 v[56:59], v213 offset:0
	v_mfma_f32_32x32x16_bf16 v[18:33], v[60:63], v[154:157], v[18:33]
	ds_read_b128 v[60:63], v213 offset:0x2000
	s_waitcnt lgkmcnt(4)
	s_waitcnt vmcnt(5)
	v_mfma_f32_32x32x16_bf16 v[34:49], v[64:67], v[150:153], v[34:49]
	v_xor_b32_e32 v214, 0xa0, v200
	ds_read_b128 v[64:67], v214 offset:0
	v_mfma_f32_32x32x16_bf16 v[18:33], v[68:71], v[150:153], v[18:33]
	ds_read_b128 v[68:71], v214 offset:0x2000
	s_waitcnt lgkmcnt(4)
	s_waitcnt vmcnt(4)
; __device__ __forceinline__ void qkt8_roll(f32x16& p0, f32x16& p1, const f32x16& negm, int kb, const bf16x8* qr) {
;   const int a0 = kb ^ (0 << 5); const bf16x8 x0 = lds_rd128<0>(a0), y0 = lds_rd128<8192>(a0);
;   const int a1 = kb ^ (1 << 5); const bf16x8 x1 = lds_rd128<0>(a1), y1 = lds_rd128<8192>(a1);
;   const int a2 = kb ^ (2 << 5); const bf16x8 x2 = lds_rd128<0>(a2), y2 = lds_rd128<8192>(a2);
;   asm volatile("s_waitcnt lgkmcnt(4)" ::: "memory"); SBAR_M();
;   p0 = __builtin_amdgcn_mfma_f32_32x32x16_bf16(x0, qr[0], negm, 0, 0, 0); p1 = __builtin_amdgcn_mfma_f32_32x32x16_bf16(y0, qr[0], negm, 0, 0, 0);
;   const int a3 = kb ^ (3 << 5); const bf16x8 x3 = lds_rd128<0>(a3), y3 = lds_rd128<8192>(a3);
;   asm volatile("s_waitcnt lgkmcnt(4)" ::: "memory"); SBAR_M();
;   p0 = __builtin_amdgcn_mfma_f32_32x32x16_bf16(x1, qr[1], p0, 0, 0, 0); p1 = __builtin_amdgcn_mfma_f32_32x32x16_bf16(y1, qr[1], p1, 0, 0, 0);
;   const int a4 = kb ^ (4 << 5); const bf16x8 x4 = lds_rd128<0>(a4), y4 = lds_rd128<8192>(a4);
;   asm volatile("s_waitcnt lgkmcnt(4)" ::: "memory"); SBAR_M();
;   p0 = __builtin_amdgcn_mfma_f32_32x32x16_bf16(x2, qr[2], p0, 0, 0, 0); p1 = __builtin_amdgcn_mfma_f32_32x32x16_bf16(y2, qr[2], p1, 0, 0, 0);
;   const int a5 = kb ^ (5 << 5); const bf16x8 x5 = lds_rd128<0>(a5), y5 = lds_rd128<8192>(a5);
;   asm volatile("s_waitcnt lgkmcnt(4)" ::: "memory"); SBAR_M();
;   p0 = __builtin_amdgcn_mfma_f32_32x32x16_bf16(x3, qr[3], p0, 0, 0, 0); p1 = __builtin_amdgcn_mfma_f32_32x32x16_bf16(y3, qr[3], p1, 0, 0, 0);
;   const int a6 = kb ^ (6 << 5); const bf16x8 x6 = lds_rd128<0>(a6), y6 = lds_rd128<8192>(a6);
;   asm volatile("s_waitcnt lgkmcnt(4)" ::: "memory"); SBAR_M();
;   p0 = __builtin_amdgcn_mfma_f32_32x32x16_bf16(x4, qr[4], p0, 0, 0, 0); p1 = __builtin_amdgcn_mfma_f32_32x32x16_bf16(y4, qr[4], p1, 0, 0, 0);
;   const int a7 = kb ^ (7 << 5); const bf16x8 x7 = lds_rd128<0>(a7), y7 = lds_rd128<8192>(a7);
;   asm volatile("s_waitcnt lgkmcnt(4)" ::: "memory"); SBAR_M();
;   p0 = __builtin_amdgcn_mfma_f32_32x32x16_bf16(x5, qr[5], p0, 0, 0, 0); p1 = __builtin_amdgcn_mfma_f32_32x32x16_bf16(y5, qr[5], p1, 0, 0, 0);
;   asm volatile("s_waitcnt lgkmcnt(2)" ::: "memory"); SBAR_M();
;   p0 = __builtin_amdgcn_mfma_f32_32x32x16_bf16(x6, qr[6], p0, 0, 0, 0); p1 = __builtin_amdgcn_mfma_f32_32x32x16_bf16(y6, qr[6], p1, 0, 0, 0);
	v_mfma_f32_32x32x16_bf16 v[34:49], v[72:75], v[146:149], v[34:49]
	v_xor_b32_e32 v215, 0xc0, v200
	ds_read_b128 v[72:75], v215 offset:0
	v_mfma_f32_32x32x16_bf16 v[18:33], v[76:79], v[146:149], v[18:33]
	ds_read_b128 v[76:79], v215 offset:0x2000
	s_waitcnt lgkmcnt(4)
	s_waitcnt vmcnt(3)
	v_mfma_f32_32x32x16_bf16 v[34:49], v[56:59], v[142:145], v[34:49]
	v_xor_b32_e32 v216, 0xe0, v200
	ds_read_b128 v[56:59], v216 offset:0
	v_mfma_f32_32x32x16_bf16 v[18:33], v[60:63], v[142:145], v[18:33]
	ds_read_b128 v[60:63], v216 offset:0x2000
	s_waitcnt lgkmcnt(4)
	s_waitcnt vmcnt(2)
	v_mfma_f32_32x32x16_bf16 v[34:49], v[64:67], v[138:141], v[34:49]
	s_waitcnt lgkmcnt(2)
	v_mfma_f32_32x32x16_bf16 v[18:33], v[68:71], v[138:141], v[18:33]
	s_waitcnt vmcnt(1)
	v_mfma_f32_32x32x16_bf16 v[34:49], v[72:75], v[134:137], v[34:49]
	s_waitcnt lgkmcnt(0)
	v_mfma_f32_32x32x16_bf16 v[18:33], v[76:79], v[134:137], v[18:33]
	v_add_u32_e32 v64, 64, v50
	v_add_u32_e32 v68, 0x60, v50
	v_mad_i64_i32 v[66:67], s[4:5], v64, s55, v[54:55]
	v_mad_i64_i32 v[54:55], s[4:5], v68, s55, v[54:55]
	v_ashrrev_i32_e32 v65, 31, v64
	v_ashrrev_i32_e32 v69, 31, v68
	s_waitcnt vmcnt(0)
	v_mfma_f32_32x32x16_bf16 v[34:49], v[56:59], v[130:133], v[34:49]
	v_lshl_add_u64 v[56:57], v[66:67], 0, v[0:1]
	v_lshl_add_u64 v[58:59], v[54:55], 0, v[0:1]
	global_load_dwordx4 v[54:57], v[56:57], off
	s_nop 0
	global_load_dwordx4 v[82:85], v[58:59], off
	v_lshlrev_b64 v[58:59], 9, v[64:65]
	v_lshl_add_u64 v[58:59], s[50:51], 0, v[58:59]
	v_lshl_add_u64 v[58:59], v[58:59], 0, v[0:1]
	s_mov_b32 s4, 0xc3480000
	v_mfma_f32_32x32x16_bf16 v[18:33], v[60:63], v[130:133], v[18:33]
	v_lshlrev_b64 v[60:61], 9, v[68:69]
	v_lshl_add_u64 v[60:61], s[50:51], 0, v[60:61]
	v_lshl_add_u64 v[62:63], v[60:61], 0, v[0:1]
	global_load_dwordx4 v[58:61], v[58:59], off
	s_nop 0
	global_load_dwordx4 v[62:65], v[62:63], off
	v_max_f32_e32 v66, v38, v38
	v_max_f32_e32 v0, v34, v34
	v_max_f32_e32 v0, v0, v66
	v_max_f32_e32 v66, v39, v39
	v_max_f32_e32 v67, v35, v35
	v_max_f32_e32 v66, v67, v66
	v_max_f32_e32 v67, v41, v41
	v_max_f32_e32 v68, v37, v37
	v_max_f32_e32 v67, v68, v67
	v_max3_f32 v68, v36, v40, v44
	v_max3_f32 v67, v67, v45, v49
	v_max3_f32 v0, v0, v42, v46
	v_max3_f32 v66, v66, v43, v47
	v_max3_f32 v68, v68, v48, v20
	v_max3_f32 v67, v67, v21, v25
	v_max3_f32 v0, v0, v18, v22
	v_max3_f32 v66, v66, v19, v23
	v_max3_f32 v68, v68, v24, v28
	v_max3_f32 v67, v67, v29, v33
	v_max3_f32 v0, v0, v26, v30
	v_max3_f32 v66, v66, v27, v31
	v_max3_f32 v67, v68, v32, v67
	v_max3_f32 v0, v0, v66, v67
	v_mov_b32_e32 v66, v0
	s_nop 1
	v_permlane32_swap_b32_e32 v0, v66
	v_max3_f32 v0, v0, v66, s4
	s_addk_i32 s6, 0x4000
	v_sub_f32_e32 v34, v34, v0
	v_sub_f32_e32 v35, v35, v0
	v_sub_f32_e32 v36, v36, v0
	v_sub_f32_e32 v37, v37, v0
	v_sub_f32_e32 v38, v38, v0
	v_sub_f32_e32 v39, v39, v0
	v_sub_f32_e32 v40, v40, v0
	v_sub_f32_e32 v41, v41, v0
	v_sub_f32_e32 v42, v42, v0
	v_sub_f32_e32 v43, v43, v0
	v_sub_f32_e32 v44, v44, v0
	v_sub_f32_e32 v45, v45, v0
	v_sub_f32_e32 v46, v46, v0
	v_sub_f32_e32 v47, v47, v0
	v_sub_f32_e32 v48, v48, v0
	v_sub_f32_e32 v49, v49, v0
	v_add_u32_e32 v198, s6, v86
	s_add_u32 s6, s42, s64
	v_exp_f32_e32 v176, v34
	v_exp_f32_e32 v188, v35
	v_exp_f32_e32 v163, v36
	v_exp_f32_e32 v177, v37
	v_exp_f32_e32 v164, v38
	v_exp_f32_e32 v175, v39
	v_exp_f32_e32 v165, v40
	v_exp_f32_e32 v174, v41
	v_exp_f32_e32 v166, v42
	v_exp_f32_e32 v173, v43
	v_exp_f32_e32 v167, v44
	v_exp_f32_e32 v172, v45
	v_exp_f32_e32 v168, v46
	v_exp_f32_e32 v171, v47
	v_exp_f32_e32 v169, v48
	v_exp_f32_e32 v170, v49
	s_addc_u32 s7, s43, 0
	v_sub_f32_e32 v67, v19, v0
	v_sub_f32_e32 v66, v18, v0
	s_waitcnt vmcnt(0)
	v_mov_b64_e32 v[18:19], s[6:7]
	v_sub_f32_e32 v81, v33, v0
	v_sub_f32_e32 v80, v32, v0
	v_sub_f32_e32 v79, v31, v0
	v_sub_f32_e32 v78, v30, v0
	v_sub_f32_e32 v77, v29, v0
	v_sub_f32_e32 v76, v28, v0
	v_sub_f32_e32 v75, v27, v0
	v_sub_f32_e32 v74, v26, v0
	v_sub_f32_e32 v73, v25, v0
	v_sub_f32_e32 v72, v24, v0
	v_sub_f32_e32 v71, v23, v0
	v_sub_f32_e32 v70, v22, v0
	v_sub_f32_e32 v69, v21, v0
	v_sub_f32_e32 v68, v20, v0
	s_waitcnt vmcnt(3)
	ds_write_b128 v201, v[54:57] offset:16384
	s_waitcnt vmcnt(2)
	ds_write_b128 v207, v[82:85] offset:16384
	s_waitcnt vmcnt(1)
	ds_write_b128 v208, v[58:61] offset:49152
	s_waitcnt vmcnt(0)
	ds_write_b128 v209, v[62:65] offset:49152
	v_add_u32_e32 v224, 0x4000, v200
	v_cmp_gt_u32_e64 s[4:5], 32, v51
	v_lshl_add_u64 v[184:185], s[6:7], 0, v[52:53]
	v_mad_i64_i32 v[186:187], s[6:7], v50, s55, v[18:19]
	v_add_co_u32_e32 v186, vcc, 0xfff60000, v186
	s_nop 1
	v_addc_co_u32_e32 v187, vcc, -1, v187, vcc
	v_mov_b32_e32 v231, 0
	v_mov_b64_e32 v[64:65], v[16:17]
	v_mov_b64_e32 v[48:49], v[16:17]
	v_mov_b64_e32 v[32:33], v[16:17]
	v_add_f32_e32 v228, 0, v0
	v_xor_b32_e32 v223, 32, v224
	v_xor_b32_e32 v222, 64, v224
	v_xor_b32_e32 v221, 0x60, v224
	v_xor_b32_e32 v220, 0x80, v224
	v_xor_b32_e32 v219, 0xa0, v224
	v_xor_b32_e32 v218, 0xc0, v224
	v_xor_b32_e32 v217, 0xe0, v224
	v_lshl_add_u32 v183, v178, 2, v179
	v_add_u32_e32 v181, v179, v182
	v_lshlrev_b32_e32 v0, 4, v87
	v_mov_b32_e32 v225, 1.0
	v_mov_b64_e32 v[62:63], v[14:15]
	v_mov_b64_e32 v[60:61], v[12:13]
	v_mov_b64_e32 v[58:59], v[10:11]
	v_mov_b64_e32 v[56:57], v[8:9]
	v_mov_b64_e32 v[54:55], v[6:7]
	v_mov_b64_e32 v[52:53], v[4:5]
	v_mov_b64_e32 v[50:51], v[2:3]
	v_mov_b64_e32 v[46:47], v[14:15]
	v_mov_b64_e32 v[44:45], v[12:13]
	v_mov_b64_e32 v[42:43], v[10:11]
	v_mov_b64_e32 v[40:41], v[8:9]
	v_mov_b64_e32 v[38:39], v[6:7]
	v_mov_b64_e32 v[36:37], v[4:5]
	v_mov_b64_e32 v[34:35], v[2:3]
	v_mov_b64_e32 v[30:31], v[14:15]
	v_mov_b64_e32 v[28:29], v[12:13]
	v_mov_b64_e32 v[26:27], v[10:11]
	v_mov_b64_e32 v[24:25], v[8:9]
	v_mov_b64_e32 v[22:23], v[6:7]
	v_mov_b64_e32 v[20:21], v[4:5]
	v_mov_b64_e32 v[18:19], v[2:3]
	v_mov_b32_e32 v197, 0
	v_mov_b32_e32 v82, 0
	v_mov_b32_e32 v83, v231
	v_mov_b32_e32 v84, v231
	v_mov_b32_e32 v85, v231
	v_mov_b32_e32 v86, v231
	v_mov_b32_e32 v87, v231
	v_mov_b32_e32 v88, v231
	v_mov_b32_e32 v89, v231
	v_mov_b32_e32 v90, v231
	v_mov_b32_e32 v91, v231
	v_mov_b32_e32 v92, v231
	v_mov_b32_e32 v93, v231
	v_mov_b32_e32 v94, v231
	v_mov_b32_e32 v95, v231
	v_mov_b32_e32 v96, v231
	v_mov_b32_e32 v97, v231
	s_waitcnt lgkmcnt(0)
	s_barrier

; #define SWAIT() do { if constexpr (SDEPTH == 2) { if constexpr (NDQ == 4) asm volatile("s_waitcnt vmcnt(3)" ::: "memory"); else if constexpr (NDQ == 8) asm volatile("s_waitcnt vmcnt(4)" ::: "memory"); else asm volatile("s_waitcnt vmcnt(5)" ::: "memory"); } \
;     else asm volatile("s_waitcnt vmcnt(0)" ::: "memory"); } while (0)
; #define RESC(a) do { if (__any((a) < 1.f)) { if (hi == 0) al_l[r32] = (a); asm volatile("s_waitcnt lgkmcnt(0)" ::: "memory"); \
;     _Pragma("unroll") for (int d = 0; d < 4; ++d) _Pragma("unroll") for (int r = 0; r < 16; ++r) o[d][r] *= al_l[crow(r, hi)]; } } while (0)
;     ...
;     __syncthreads(); SWAIT(); SWRITE(0, SE);
;     RESC(alB); __syncthreads();
.LBB0_449:
	s_waitcnt vmcnt(0)
	v_cmp_gt_f32_e32 vcc, 1.0, v229
	s_waitcnt vmcnt(3)
	ds_write_b128 v201, v[66:69] offset:16384
	s_waitcnt vmcnt(2)
	ds_write_b128 v207, v[70:73] offset:16384
	s_waitcnt vmcnt(1)
	ds_write_b128 v208, v[74:77] offset:32768
	s_waitcnt vmcnt(0)
	ds_write_b128 v209, v[78:81] offset:32768
	s_cbranch_vccz .LBB0_453
	s_and_saveexec_b64 s[10:11], s[4:5]
	ds_write_b32 v183, v229 offset:128
	s_or_b64 exec, exec, s[10:11]
	s_waitcnt lgkmcnt(0)
	ds_read_b128 v[66:69], v181 offset:224
	ds_read_b128 v[70:73], v181 offset:192
	ds_read_b128 v[74:77], v181 offset:160
	ds_read_b128 v[78:81], v181 offset:128
	s_waitcnt lgkmcnt(3)
	v_pk_mul_f32 v[16:17], v[16:17], v[68:69]
	s_waitcnt lgkmcnt(2)
	v_pk_mul_f32 v[12:13], v[12:13], v[72:73]
	s_waitcnt lgkmcnt(1)
	v_pk_mul_f32 v[8:9], v[8:9], v[76:77]
	s_waitcnt lgkmcnt(0)
	v_pk_mul_f32 v[4:5], v[4:5], v[80:81]
	v_pk_mul_f32 v[14:15], v[14:15], v[66:67]
	v_pk_mul_f32 v[10:11], v[10:11], v[70:71]
	v_pk_mul_f32 v[6:7], v[6:7], v[74:75]
	v_pk_mul_f32 v[2:3], v[2:3], v[78:79]
	v_pk_mul_f32 v[64:65], v[64:65], v[68:69]
	v_pk_mul_f32 v[60:61], v[60:61], v[72:73]
	v_pk_mul_f32 v[56:57], v[56:57], v[76:77]
	v_pk_mul_f32 v[52:53], v[52:53], v[80:81]
	v_pk_mul_f32 v[62:63], v[62:63], v[66:67]
	v_pk_mul_f32 v[58:59], v[58:59], v[70:71]
	v_pk_mul_f32 v[54:55], v[54:55], v[74:75]
	v_pk_mul_f32 v[50:51], v[50:51], v[78:79]
	v_pk_mul_f32 v[48:49], v[48:49], v[68:69]
	v_pk_mul_f32 v[44:45], v[44:45], v[72:73]
	v_pk_mul_f32 v[40:41], v[40:41], v[76:77]
	v_pk_mul_f32 v[36:37], v[36:37], v[80:81]
	v_pk_mul_f32 v[46:47], v[46:47], v[66:67]
	v_pk_mul_f32 v[42:43], v[42:43], v[70:71]
	v_pk_mul_f32 v[38:39], v[38:39], v[74:75]
	v_pk_mul_f32 v[34:35], v[34:35], v[78:79]
	v_pk_mul_f32 v[32:33], v[32:33], v[68:69]
	v_pk_mul_f32 v[28:29], v[28:29], v[72:73]
	v_pk_mul_f32 v[24:25], v[24:25], v[76:77]
	v_pk_mul_f32 v[20:21], v[20:21], v[80:81]
	v_pk_mul_f32 v[30:31], v[30:31], v[66:67]
	v_pk_mul_f32 v[26:27], v[26:27], v[70:71]
	v_pk_mul_f32 v[22:23], v[22:23], v[74:75]
	v_pk_mul_f32 v[18:19], v[18:19], v[78:79]

; #define SWAIT() do { if constexpr (SDEPTH == 2) { if constexpr (NDQ == 4) asm volatile("s_waitcnt vmcnt(3)" ::: "memory"); else if constexpr (NDQ == 8) asm volatile("s_waitcnt vmcnt(4)" ::: "memory"); else asm volatile("s_waitcnt vmcnt(5)" ::: "memory"); } \
;     else asm volatile("s_waitcnt vmcnt(0)" ::: "memory"); } while (0)
; #define RESC(a) do { if (__any((a) < 1.f)) { if (hi == 0) al_l[r32] = (a); asm volatile("s_waitcnt lgkmcnt(0)" ::: "memory"); \
;     _Pragma("unroll") for (int d = 0; d < 4; ++d) _Pragma("unroll") for (int r = 0; r < 16; ++r) o[d][r] *= al_l[crow(r, hi)]; } } while (0)
;     ...
;     __syncthreads(); SWAIT(); SWRITE(1, SO);
;     RESC(alA); __syncthreads();
.LBB0_455:
	s_waitcnt vmcnt(0)
	v_cmp_gt_f32_e32 vcc, 1.0, v162
	s_waitcnt vmcnt(3)
	ds_write_b128 v201, v[98:101]
	s_waitcnt vmcnt(2)
	ds_write_b128 v207, v[102:105]
	s_waitcnt vmcnt(1)
	ds_write_b128 v208, v[106:109] offset:49152
	s_waitcnt vmcnt(0)
	ds_write_b128 v209, v[110:113] offset:49152
	s_cbranch_vccz .LBB0_459
	s_and_saveexec_b64 s[10:11], s[4:5]
	ds_write_b32 v183, v162 offset:128
	s_or_b64 exec, exec, s[10:11]
	s_waitcnt lgkmcnt(0)
	ds_read_b128 v[98:101], v181 offset:224
	ds_read_b128 v[102:105], v181 offset:192
	ds_read_b128 v[106:109], v181 offset:160
	ds_read_b128 v[110:113], v181 offset:128
	s_waitcnt lgkmcnt(3)
	v_pk_mul_f32 v[16:17], v[16:17], v[100:101]
	s_waitcnt lgkmcnt(2)
	v_pk_mul_f32 v[12:13], v[12:13], v[104:105]
	s_waitcnt lgkmcnt(1)
	v_pk_mul_f32 v[8:9], v[8:9], v[108:109]
	s_waitcnt lgkmcnt(0)
	v_pk_mul_f32 v[4:5], v[4:5], v[112:113]
	v_pk_mul_f32 v[14:15], v[14:15], v[98:99]
	v_pk_mul_f32 v[10:11], v[10:11], v[102:103]
	v_pk_mul_f32 v[6:7], v[6:7], v[106:107]
	v_pk_mul_f32 v[2:3], v[2:3], v[110:111]
	v_pk_mul_f32 v[64:65], v[64:65], v[100:101]
	v_pk_mul_f32 v[60:61], v[60:61], v[104:105]
	v_pk_mul_f32 v[56:57], v[56:57], v[108:109]
	v_pk_mul_f32 v[52:53], v[52:53], v[112:113]
	v_pk_mul_f32 v[62:63], v[62:63], v[98:99]
	v_pk_mul_f32 v[58:59], v[58:59], v[102:103]
	v_pk_mul_f32 v[54:55], v[54:55], v[106:107]
	v_pk_mul_f32 v[50:51], v[50:51], v[110:111]
	v_pk_mul_f32 v[48:49], v[48:49], v[100:101]
	v_pk_mul_f32 v[44:45], v[44:45], v[104:105]
	v_pk_mul_f32 v[40:41], v[40:41], v[108:109]
	v_pk_mul_f32 v[36:37], v[36:37], v[112:113]
	v_pk_mul_f32 v[46:47], v[46:47], v[98:99]
	v_pk_mul_f32 v[42:43], v[42:43], v[102:103]
	v_pk_mul_f32 v[38:39], v[38:39], v[106:107]
	v_pk_mul_f32 v[34:35], v[34:35], v[110:111]
	v_pk_mul_f32 v[32:33], v[32:33], v[100:101]
	v_pk_mul_f32 v[28:29], v[28:29], v[104:105]
	v_pk_mul_f32 v[24:25], v[24:25], v[108:109]
	v_pk_mul_f32 v[20:21], v[20:21], v[112:113]
	v_pk_mul_f32 v[30:31], v[30:31], v[98:99]
	v_pk_mul_f32 v[26:27], v[26:27], v[102:103]
	v_pk_mul_f32 v[22:23], v[22:23], v[106:107]
	v_pk_mul_f32 v[18:19], v[18:19], v[110:111]

; #define SBAR() __builtin_amdgcn_sched_barrier(0)
; #define BIASADD(P0, P1, kt0) do { if constexpr (BIAS) { const int dlo_ = (kt0) - q0 - 255, dhi_ = (kt0) + 63 - q0; \
;     if (!(dlo_ >= 1024) && !(dhi_ <= -1024)) { const float* tb_ = tbl_l + ((kt0) - qlane + TOFF + 4 * hi); \
;       _Pragma("unroll") for (int r = 0; r < 16; ++r) { P0[r] += tb_[(r & 3) + 8 * (r >> 2)]; P1[r] += tb_[32 + (r & 3) + 8 * (r >> 2)]; } } } } while (0)
; #define NEGM_UPD(kt0) do { float nmj_ = -mC; if constexpr (BIAS) { const int dlo_ = (kt0) - q0 - 255, dhi_ = (kt0) + 63 - q0; if (dlo_ >= 1024) nmj_ += cb_hi; else if (dhi_ <= -1024) nmj_ += cb_lo; } \
;     if (__any(nmj_ != nm_cur)) { nm_cur = nmj_; _Pragma("unroll") for (int r = 0; r < 16; ++r) negm[r] = nmj_; } } while (0)
; #define QKT(P0, P1, KOFF) do { if constexpr (NDQ == 8 && NQL == 0) qkt8_roll(P0, P1, negm, kb0 + (KOFF), qr); \
;     else if constexpr (NDQ == 12 && NQL == 4) qkt12_roll(P0, P1, negm, kb0 + (KOFF), qa0, qr); else qkt<NDQ, NQL>(P0, P1, negm, K_lds + (KOFF), qr, qls, r32, hi); } while (0)
; template <bool EXP1 = true>
; __device__ __forceinline__ void finishSM(f32x16& p0, f32x16& p1, float alpha, float& l_reg, bf16x8& pa0, bf16x8& pa1, bf16x8& pa2, bf16x8& pa3) {
;   if constexpr (EXP1) {
; #pragma unroll
;   for (int r = 0; r < 16; ++r) p1[r] = __builtin_amdgcn_exp2f(p1[r]);
;   }
;   float sm_[4] = {p0[0], p0[1], p0[2], p0[3]};
; #pragma unroll
;   for (int r = 4; r < 16; ++r) sm_[r & 3] += p0[r];
; #pragma unroll
;   for (int r = 0; r < 16; ++r) sm_[r & 3] += p1[r];
;   float ps = (sm_[0] + sm_[1]) + (sm_[2] + sm_[3]);
;   { auto rr = __builtin_amdgcn_permlane32_swap(__float_as_uint(ps), __float_as_uint(ps), false, false);
;     ps = __uint_as_float(rr[0]) + __uint_as_float(rr[1]); }
;   l_reg = l_reg * alpha + ps;
;     ...
;   PK4(p0, 0, pa0); PK4(p0, 8, pa1); PK4(p1, 0, pa2); PK4(p1, 8, pa3);
;     ...
; }
;     ...
;   NEGM_UPD(kbeg + (NT - 1) * KVBLK); SBAR(); QKT(pB0, pB1, SHM_K);
;   finishSM<!SLICED>(pA0, pA1, alA, l_reg, pa0, pa1, pa2, pa3); SBAR();
;   pv_d0(o, vb0, pa0, pa1, pa2, pa3); BIASADD(pB0, pB1, kbeg + (NT - 1) * KVBLK); partialSM<false>(pB0, pB1, mC, alB);
.LBB0_463:
	v_lshl_add_u64 v[252:253], v[186:187], 0, v[0:1]
	v_add_co_u32_e64 v252, s[6:7], s78, v252
	s_nop 1
	v_addc_co_u32_e64 v253, s[6:7], 0, v253, s[6:7]
	v_cmp_neq_f32_e64 s[6:7], v231, -v228
	s_cmp_eq_u64 s[6:7], 0
	s_cselect_b64 s[6:7], -1, 0
	v_cndmask_b32_e64 v97, -v228, v97, s[6:7]
	v_cndmask_b32_e64 v96, -v228, v96, s[6:7]
	v_cndmask_b32_e64 v95, -v228, v95, s[6:7]
	v_cndmask_b32_e64 v94, -v228, v94, s[6:7]
	v_cndmask_b32_e64 v93, -v228, v93, s[6:7]
	v_cndmask_b32_e64 v92, -v228, v92, s[6:7]
	v_cndmask_b32_e64 v91, -v228, v91, s[6:7]
	v_cndmask_b32_e64 v90, -v228, v90, s[6:7]
	v_cndmask_b32_e64 v89, -v228, v89, s[6:7]
	v_cndmask_b32_e64 v88, -v228, v88, s[6:7]
	v_cndmask_b32_e64 v87, -v228, v87, s[6:7]
	v_cndmask_b32_e64 v86, -v228, v86, s[6:7]
	v_cndmask_b32_e64 v85, -v228, v85, s[6:7]
	v_cndmask_b32_e64 v84, -v228, v84, s[6:7]
	v_cndmask_b32_e64 v83, -v228, v83, s[6:7]
	v_cndmask_b32_e64 v82, -v228, v82, s[6:7]
	ds_read_b128 v[114:117], v224 offset:0
	ds_read_b128 v[118:121], v224 offset:0x2000
	ds_read_b128 v[122:125], v223 offset:0
	ds_read_b128 v[126:129], v223 offset:0x2000
	ds_read_b128 v[184:187], v222 offset:0
	ds_read_b128 v[208:211], v222 offset:0x2000
	s_waitcnt lgkmcnt(4)
	s_nop 1
	v_mfma_f32_32x32x16_bf16 v[98:113], v[114:117], v[158:161], v[82:97]
	ds_read_b128 v[114:117], v221 offset:0
	v_mfma_f32_32x32x16_bf16 v[82:97], v[118:121], v[158:161], v[82:97]
	ds_read_b128 v[118:121], v221 offset:0x2000
	s_waitcnt lgkmcnt(4)
	v_mfma_f32_32x32x16_bf16 v[98:113], v[122:125], v[154:157], v[98:113]
	ds_read_b128 v[122:125], v220 offset:0
	v_mfma_f32_32x32x16_bf16 v[82:97], v[126:129], v[154:157], v[82:97]
	ds_read_b128 v[126:129], v220 offset:0x2000
	s_waitcnt lgkmcnt(4)
	v_mfma_f32_32x32x16_bf16 v[98:113], v[184:187], v[150:153], v[98:113]
	v_mfma_f32_32x32x16_bf16 v[82:97], v[208:211], v[150:153], v[82:97]
	ds_read_b128 v[150:153], v219 offset:0
	ds_read_b128 v[154:157], v219 offset:0x2000
	s_waitcnt lgkmcnt(4)
	v_mfma_f32_32x32x16_bf16 v[98:113], v[114:117], v[146:149], v[98:113]
	ds_read_b128 v[114:117], v218 offset:0
	v_mfma_f32_32x32x16_bf16 v[82:97], v[118:121], v[146:149], v[82:97]
	ds_read_b128 v[118:121], v218 offset:0x2000
	s_waitcnt lgkmcnt(4)
	v_mfma_f32_32x32x16_bf16 v[98:113], v[122:125], v[142:145], v[98:113]
	ds_read_b128 v[122:125], v217 offset:0
	v_mfma_f32_32x32x16_bf16 v[82:97], v[126:129], v[142:145], v[82:97]
	ds_read_b128 v[126:129], v217 offset:0x2000
	s_waitcnt lgkmcnt(4)
	v_mfma_f32_32x32x16_bf16 v[98:113], v[150:153], v[138:141], v[98:113]
	s_waitcnt lgkmcnt(2)
	v_mfma_f32_32x32x16_bf16 v[82:97], v[154:157], v[138:141], v[82:97]
	v_mfma_f32_32x32x16_bf16 v[98:113], v[114:117], v[134:137], v[98:113]
	s_waitcnt lgkmcnt(0)
	v_mfma_f32_32x32x16_bf16 v[82:97], v[118:121], v[134:137], v[82:97]
	v_exp_f32_e32 v115, v66
	v_exp_f32_e32 v116, v67
	v_exp_f32_e32 v117, v68
	v_exp_f32_e32 v118, v69
	v_mfma_f32_32x32x16_bf16 v[98:113], v[122:125], v[130:133], v[98:113]
	v_exp_f32_e32 v119, v70
	v_exp_f32_e32 v120, v71
	v_exp_f32_e32 v121, v72
	v_exp_f32_e32 v122, v73
	v_add_f32_e32 v0, v164, v176
	v_add_f32_e32 v66, v175, v188
	v_add_f32_e32 v67, v165, v163
	v_add_f32_e32 v68, v174, v177
	v_mfma_f32_32x32x16_bf16 v[82:97], v[126:129], v[130:133], v[82:97]
	v_exp_f32_e32 v123, v74
	v_exp_f32_e32 v124, v75
	v_exp_f32_e32 v125, v76
	v_exp_f32_e32 v126, v77
	v_add_f32_e32 v0, v166, v0
	v_add_f32_e32 v66, v173, v66
	v_add_f32_e32 v67, v167, v67
	v_add_f32_e32 v68, v172, v68
	v_exp_f32_e32 v127, v78
	v_exp_f32_e32 v128, v79
	v_exp_f32_e32 v129, v80
	v_exp_f32_e32 v81, v81
	v_add_f32_e32 v0, v168, v0
	v_add_f32_e32 v66, v171, v66
	v_add_f32_e32 v67, v169, v67
	v_add_f32_e32 v68, v170, v68
	v_add_f32_e32 v0, v0, v115
	v_add_f32_e32 v66, v66, v116
	v_add_f32_e32 v67, v67, v117
	v_add_f32_e32 v68, v68, v118
	v_add_f32_e32 v0, v119, v0
	v_add_f32_e32 v66, v120, v66
	v_add_f32_e32 v67, v121, v67
	v_add_f32_e32 v68, v122, v68
	v_add_f32_e32 v0, v123, v0
	v_add_f32_e32 v66, v124, v66
	v_add_f32_e32 v67, v125, v67
	v_add_f32_e32 v68, v126, v68
	v_add_f32_e32 v0, v127, v0
	v_add_f32_e32 v66, v128, v66
	v_add_f32_e32 v67, v129, v67
	v_add_f32_e32 v68, v81, v68
	v_add_f32_e32 v0, v0, v66
	v_add_f32_e32 v66, v67, v68
	v_add_f32_e32 v0, v0, v66
	v_mov_b32_e32 v114, v0
	v_cvt_pk_bf16_f32 v66, v176, v188
	v_cvt_pk_bf16_f32 v67, v163, v177
	v_cvt_pk_bf16_f32 v68, v164, v175
	s_nop 1
	v_permlane32_swap_b32_e32 v0, v114
	v_cvt_pk_bf16_f32 v69, v165, v174
	v_permlane32_swap_b32_e32 v66, v68
	v_cvt_pk_bf16_f32 v70, v166, v173
	v_cvt_pk_bf16_f32 v71, v167, v172
	v_cvt_pk_bf16_f32 v72, v168, v171
	v_cvt_pk_bf16_f32 v73, v169, v170
	v_cvt_pk_bf16_f32 v74, v115, v116
	v_cvt_pk_bf16_f32 v75, v117, v118
	v_cvt_pk_bf16_f32 v76, v119, v120
	v_cvt_pk_bf16_f32 v77, v121, v122
	v_cvt_pk_bf16_f32 v78, v123, v124
	v_cvt_pk_bf16_f32 v79, v125, v126
	v_cvt_pk_bf16_f32 v80, v127, v128
	v_cvt_pk_bf16_f32 v81, v129, v81
	v_permlane32_swap_b32_e32 v67, v69
	v_permlane32_swap_b32_e32 v70, v72
	v_permlane32_swap_b32_e32 v71, v73
	v_permlane32_swap_b32_e32 v74, v76
	v_permlane32_swap_b32_e32 v75, v77
	v_permlane32_swap_b32_e32 v78, v80
	v_permlane32_swap_b32_e32 v79, v81
	ds_read_b64_tr_b16 v[116:117], v199 offset:0
	ds_read_b64_tr_b16 v[118:119], v199 offset:0x800
	ds_read_b64_tr_b16 v[120:121], v199 offset:0x1000
	ds_read_b64_tr_b16 v[122:123], v199 offset:0x1800
	ds_read_b64_tr_b16 v[124:125], v199 offset:0x2000
	ds_read_b64_tr_b16 v[126:127], v199 offset:0x2800
	ds_read_b64_tr_b16 v[128:129], v199 offset:0x3000
	ds_read_b64_tr_b16 v[130:131], v199 offset:0x3800
	ds_read_b64_tr_b16 v[132:133], v199 offset:0x200
	ds_read_b64_tr_b16 v[134:135], v199 offset:0xa00
	s_waitcnt lgkmcnt(8)
; __device__ __forceinline__ void pv_d0(f32x16* o, int vb, bf16x8 pa0, bf16x8 pa1, bf16x8 pa2, bf16x8 pa3) {
;     ...
;   const s16x4 l0 = tr_read<v_rd_off(0, 0, 0)>(vb), h0 = tr_read<v_rd_off(0, 0, 1)>(vb);
;   const s16x4 l1 = tr_read<v_rd_off(0, 1, 0)>(vb), h1 = tr_read<v_rd_off(0, 1, 1)>(vb);
;   const s16x4 l2 = tr_read<v_rd_off(0, 2, 0)>(vb), h2 = tr_read<v_rd_off(0, 2, 1)>(vb);
;   const s16x4 l3 = tr_read<v_rd_off(0, 3, 0)>(vb), h3 = tr_read<v_rd_off(0, 3, 1)>(vb);
;   const s16x4 l4 = tr_read<v_rd_off(1, 0, 0)>(vb), h4 = tr_read<v_rd_off(1, 0, 1)>(vb);
;   asm volatile("s_waitcnt lgkmcnt(8)" ::: "memory"); SBAR();
;   o[0] = __builtin_amdgcn_mfma_f32_32x32x16_bf16(pa0, PK(l0, h0), o[0], 0, 0, 0);
;   const s16x4 l5 = tr_read<v_rd_off(1, 1, 0)>(vb), h5 = tr_read<v_rd_off(1, 1, 1)>(vb);
;   asm volatile("s_waitcnt lgkmcnt(8)" ::: "memory"); SBAR();
;   o[0] = __builtin_amdgcn_mfma_f32_32x32x16_bf16(pa1, PK(l1, h1), o[0], 0, 0, 0);
;   const s16x4 l6 = tr_read<v_rd_off(1, 2, 0)>(vb), h6 = tr_read<v_rd_off(1, 2, 1)>(vb);
;   asm volatile("s_waitcnt lgkmcnt(8)" ::: "memory"); SBAR();
;   o[0] = __builtin_amdgcn_mfma_f32_32x32x16_bf16(pa2, PK(l2, h2), o[0], 0, 0, 0);
;   const s16x4 l7 = tr_read<v_rd_off(1, 3, 0)>(vb), h7 = tr_read<v_rd_off(1, 3, 1)>(vb);
;   asm volatile("s_waitcnt lgkmcnt(8)" ::: "memory"); SBAR();
;   o[0] = __builtin_amdgcn_mfma_f32_32x32x16_bf16(pa3, PK(l3, h3), o[0], 0, 0, 0);
;   const s16x4 l8 = tr_read<v_rd_off(2, 0, 0)>(vb), h8 = tr_read<v_rd_off(2, 0, 1)>(vb);
;   asm volatile("s_waitcnt lgkmcnt(8)" ::: "memory"); SBAR();
;   o[1] = __builtin_amdgcn_mfma_f32_32x32x16_bf16(pa0, PK(l4, h4), o[1], 0, 0, 0);
;   const s16x4 l9 = tr_read<v_rd_off(2, 1, 0)>(vb), h9 = tr_read<v_rd_off(2, 1, 1)>(vb);
;   asm volatile("s_waitcnt lgkmcnt(8)" ::: "memory"); SBAR();
;   o[1] = __builtin_amdgcn_mfma_f32_32x32x16_bf16(pa1, PK(l5, h5), o[1], 0, 0, 0);
;   const s16x4 l10 = tr_read<v_rd_off(2, 2, 0)>(vb), h10 = tr_read<v_rd_off(2, 2, 1)>(vb);
;   asm volatile("s_waitcnt lgkmcnt(8)" ::: "memory"); SBAR();
;   o[1] = __builtin_amdgcn_mfma_f32_32x32x16_bf16(pa2, PK(l6, h6), o[1], 0, 0, 0);
;   const s16x4 l11 = tr_read<v_rd_off(2, 3, 0)>(vb), h11 = tr_read<v_rd_off(2, 3, 1)>(vb);
;   asm volatile("s_waitcnt lgkmcnt(8)" ::: "memory"); SBAR();
;   o[1] = __builtin_amdgcn_mfma_f32_32x32x16_bf16(pa3, PK(l7, h7), o[1], 0, 0, 0);
	s_nop 0
	v_mfma_f32_32x32x16_bf16 v[2:17], v[66:69], v[116:119], v[2:17]
	ds_read_b64_tr_b16 v[116:117], v199 offset:0x1200
	ds_read_b64_tr_b16 v[118:119], v199 offset:0x1a00
	s_waitcnt lgkmcnt(8)
	v_mfma_f32_32x32x16_bf16 v[2:17], v[70:73], v[120:123], v[2:17]
	ds_read_b64_tr_b16 v[120:121], v199 offset:0x2200
	ds_read_b64_tr_b16 v[122:123], v199 offset:0x2a00
	s_waitcnt lgkmcnt(8)
	v_mfma_f32_32x32x16_bf16 v[2:17], v[74:77], v[124:127], v[2:17]
	ds_read_b64_tr_b16 v[124:125], v199 offset:0x3200
	ds_read_b64_tr_b16 v[126:127], v199 offset:0x3a00
	s_waitcnt lgkmcnt(8)
	v_mfma_f32_32x32x16_bf16 v[2:17], v[78:81], v[128:131], v[2:17]
	ds_read_b64_tr_b16 v[128:129], v199 offset:0x400
	ds_read_b64_tr_b16 v[130:131], v199 offset:0xc00
	s_waitcnt lgkmcnt(8)
	v_mfma_f32_32x32x16_bf16 v[50:65], v[66:69], v[132:135], v[50:65]
	ds_read_b64_tr_b16 v[132:133], v199 offset:0x1400
	ds_read_b64_tr_b16 v[134:135], v199 offset:0x1c00
	s_waitcnt lgkmcnt(8)
	v_mfma_f32_32x32x16_bf16 v[50:65], v[70:73], v[116:119], v[50:65]
	ds_read_b64_tr_b16 v[116:117], v199 offset:0x2400
	ds_read_b64_tr_b16 v[118:119], v199 offset:0x2c00
	s_waitcnt lgkmcnt(8)
	v_mfma_f32_32x32x16_bf16 v[50:65], v[74:77], v[120:123], v[50:65]
	ds_read_b64_tr_b16 v[120:121], v199 offset:0x3400
	ds_read_b64_tr_b16 v[122:123], v199 offset:0x3c00
	s_waitcnt lgkmcnt(8)
	v_mfma_f32_32x32x16_bf16 v[50:65], v[78:81], v[124:127], v[50:65]
	ds_read_b64_tr_b16 v[124:125], v199 offset:0x600
	ds_read_b64_tr_b16 v[126:127], v199 offset:0xe00
	s_waitcnt lgkmcnt(8)
	v_mfma_f32_32x32x16_bf16 v[34:49], v[66:69], v[128:131], v[34:49]
	ds_read_b64_tr_b16 v[128:129], v199 offset:0x1600
	ds_read_b64_tr_b16 v[130:131], v199 offset:0x1e00
	s_waitcnt lgkmcnt(8)
	v_mfma_f32_32x32x16_bf16 v[34:49], v[70:73], v[132:135], v[34:49]
	ds_read_b64_tr_b16 v[132:133], v199 offset:0x2600
	ds_read_b64_tr_b16 v[134:135], v199 offset:0x2e00
	s_waitcnt lgkmcnt(8)
	v_mfma_f32_32x32x16_bf16 v[34:49], v[74:77], v[116:119], v[34:49]
	ds_read_b64_tr_b16 v[116:117], v199 offset:0x3600
	ds_read_b64_tr_b16 v[118:119], v199 offset:0x3e00
	s_waitcnt lgkmcnt(8)
	v_mfma_f32_32x32x16_bf16 v[34:49], v[78:81], v[120:123], v[34:49]
	s_waitcnt lgkmcnt(6)
	v_mfma_f32_32x32x16_bf16 v[18:33], v[66:69], v[124:127], v[18:33]
	s_waitcnt lgkmcnt(4)
	v_mfma_f32_32x32x16_bf16 v[18:33], v[70:73], v[128:131], v[18:33]
	s_waitcnt lgkmcnt(2)
	v_mfma_f32_32x32x16_bf16 v[18:33], v[74:77], v[132:135], v[18:33]
	s_waitcnt lgkmcnt(0)
	v_max_f32_e32 v66, v102, v102
	v_max_f32_e32 v67, v98, v98
	v_max_f32_e32 v66, v67, v66
	v_max_f32_e32 v67, v103, v103
	v_max_f32_e32 v68, v99, v99
	v_max_f32_e32 v67, v68, v67
	v_max_f32_e32 v68, v105, v105
	v_max_f32_e32 v69, v101, v101
	v_max_f32_e32 v68, v69, v68
	v_max3_f32 v69, v100, v104, v108
	v_max3_f32 v68, v68, v109, v113
	v_max3_f32 v66, v66, v106, v110
	v_max3_f32 v67, v67, v107, v111
	v_max3_f32 v69, v69, v112, v84
	v_max3_f32 v68, v68, v85, v89
	v_max3_f32 v66, v66, v82, v86
	v_max3_f32 v67, v67, v83, v87
	v_max3_f32 v69, v69, v88, v92
	v_max3_f32 v68, v68, v93, v97
	v_mfma_f32_32x32x16_bf16 v[18:33], v[78:81], v[116:119], v[18:33]
	v_max3_f32 v66, v66, v90, v94
	v_max3_f32 v67, v67, v91, v95
	v_max3_f32 v68, v69, v96, v68
	v_max3_f32 v66, v66, v67, v68
	v_mov_b32_e32 v67, v66
	s_nop 1
	v_permlane32_swap_b32_e32 v66, v67
	v_max_f32_e32 v67, v67, v67
	v_max_f32_e32 v66, v66, v66
	v_max_f32_e32 v66, v66, v67
	v_cmp_ge_f32_e32 vcc, s48, v66
	s_cmp_lg_u64 vcc, exec
	v_mov_b32_e32 v115, 1.0
	s_cbranch_scc1 .LBB0_471
